# k15 + GEMM wave groups stay staggered across tile epilogues (alignment barriers removed, one extra barrier for the leading group at phase exit)
# baseline (speedup 1.0000x reference)
; __device__ __forceinline__ unsigned cvt_pk_bf16(float lo, float hi) { unsigned r; asm volatile("v_cvt_pk_bf16_f32 %0, %1, %2" : "=v"(r) : "v"(lo), "v"(hi)); return r; }
;     __device__ __forceinline__ void operator()(const f32x4 (&acc)[2][2][4][2], const Unit& u, int wr, int wc, int fr, int fq) const {
;         const int row0 = u.pm * BM + wr * 64 + fr; const int col0 = u.pn * HALF + wc * 32 + 8 * fq;
; #pragma unroll
;         for (int ai = 0; ai < 2; ++ai)
; #pragma unroll
;             for (int m = 0; m < 4; ++m) {
;                 bf16_t* rowp = O + (size_t)(row0 + ai * HALF + m * 16) * ldc + col0;
;                 const f32x4 g0 = acc[ai][0][m][0], g1 = acc[ai][0][m][1], u0 = acc[ai][1][m][0], u1 = acc[ai][1][m][1];
;                 const f32x2 a = silu_mul_pk((f32x2){g0[0], g0[1]}, (f32x2){u0[0], u0[1]}), b = silu_mul_pk((f32x2){g0[2], g0[3]}, (f32x2){u0[2], u0[3]});
;                 const f32x2 c = silu_mul_pk((f32x2){g1[0], g1[1]}, (f32x2){u1[0], u1[1]}), d = silu_mul_pk((f32x2){g1[2], g1[3]}, (f32x2){u1[2], u1[3]});
;                 u32x4 w; w.x = cvt_pk_bf16(a.x, a.y); w.y = cvt_pk_bf16(b.x, b.y); w.z = cvt_pk_bf16(c.x, c.y); w.w = cvt_pk_bf16(d.x, d.y);
;                 *(u32x4*)rowp = w;
;             }
.LBB0_51:
	v_pk_mul_f32 v[162:163], v[124:125], s[16:17] op_sel_hi:[1,0]
	v_pk_mul_f32 v[164:165], v[126:127], s[16:17] op_sel_hi:[1,0]
	v_exp_f32_e32 v162, v162
	v_exp_f32_e32 v163, v163
	v_exp_f32_e32 v164, v164
	v_exp_f32_e32 v165, v165
	v_lshl_or_b32 v152, s6, 7, v143
	v_pk_add_f32 v[162:163], v[162:163], 1.0 op_sel_hi:[1,0]
	v_lshl_add_u32 v159, s82, 8, v137
	v_rcp_f32_e32 v162, v162
	v_rcp_f32_e32 v163, v163
	v_pk_add_f32 v[164:165], v[164:165], 1.0 op_sel_hi:[1,0]
	v_ashrrev_i32_e32 v153, 31, v152
	v_rcp_f32_e32 v164, v164
	v_rcp_f32_e32 v165, v165
	v_pk_mul_f32 v[124:125], v[124:125], v[162:163]
	v_pk_mul_f32 v[162:163], v[122:123], s[16:17] op_sel_hi:[1,0]
	v_pk_mul_f32 v[116:117], v[124:125], v[116:117]
	v_pk_mul_f32 v[124:125], v[126:127], v[164:165]
	v_pk_mul_f32 v[126:127], v[120:121], s[16:17] op_sel_hi:[1,0]
	v_exp_f32_e32 v162, v162
	v_exp_f32_e32 v126, v126
	v_exp_f32_e32 v127, v127
	v_exp_f32_e32 v163, v163
	v_mov_b64_e32 v[154:155], s[46:47]
	v_mad_i64_i32 v[160:161], s[6:7], v159, s97, v[154:155]
	v_pk_add_f32 v[126:127], v[126:127], 1.0 op_sel_hi:[1,0]
	v_pk_add_f32 v[162:163], v[162:163], 1.0 op_sel_hi:[1,0]
	v_rcp_f32_e32 v126, v126
	v_rcp_f32_e32 v127, v127
	v_rcp_f32_e32 v162, v162
	v_rcp_f32_e32 v163, v163
	v_lshlrev_b64 v[152:153], 1, v[152:153]
	v_pk_mul_f32 v[120:121], v[120:121], v[126:127]
	v_lshl_add_u64 v[160:161], v[160:161], 0, v[152:153]
	v_pk_mul_f32 v[120:121], v[120:121], v[112:113]
	v_pk_mul_f32 v[112:113], v[122:123], v[162:163]
	v_pk_mul_f32 v[118:119], v[124:125], v[118:119]
	v_pk_mul_f32 v[122:123], v[112:113], v[114:115]
	v_cvt_pk_bf16_f32 v112, v116, v117
	v_cvt_pk_bf16_f32 v113, v118, v119
	v_cvt_pk_bf16_f32 v114, v120, v121
	v_pk_mul_f32 v[116:117], v[110:111], s[16:17] op_sel_hi:[1,0]
	v_cvt_pk_bf16_f32 v115, v122, v123
	global_store_dwordx4 v[160:161], v[112:115], off
	v_exp_f32_e32 v116, v116
	v_exp_f32_e32 v117, v117
	v_pk_mul_f32 v[114:115], v[108:109], s[16:17] op_sel_hi:[1,0]
	v_or_b32_e32 v112, 16, v159
	v_exp_f32_e32 v114, v114
	v_exp_f32_e32 v115, v115
	v_pk_add_f32 v[116:117], v[116:117], 1.0 op_sel_hi:[1,0]
	v_mad_i64_i32 v[112:113], s[6:7], v112, s97, v[154:155]
	v_pk_add_f32 v[114:115], v[114:115], 1.0 op_sel_hi:[1,0]
	v_rcp_f32_e32 v116, v116
	v_rcp_f32_e32 v114, v114
	v_rcp_f32_e32 v115, v115
	v_rcp_f32_e32 v117, v117
	v_lshl_add_u64 v[112:113], v[112:113], 0, v[152:153]
	s_andn2_b64 vcc, exec, s[0:1]
	v_pk_mul_f32 v[108:109], v[108:109], v[114:115]
	v_pk_mul_f32 v[114:115], v[106:107], s[16:17] op_sel_hi:[1,0]
	v_pk_mul_f32 v[100:101], v[108:109], v[100:101]
	v_pk_mul_f32 v[108:109], v[110:111], v[116:117]
	v_pk_mul_f32 v[110:111], v[104:105], s[16:17] op_sel_hi:[1,0]
	v_exp_f32_e32 v114, v114
	v_exp_f32_e32 v110, v110
	v_exp_f32_e32 v111, v111
	v_exp_f32_e32 v115, v115
	v_pk_mul_f32 v[102:103], v[108:109], v[102:103]
	s_mov_b64 s[0:1], -1
	v_pk_add_f32 v[110:111], v[110:111], 1.0 op_sel_hi:[1,0]
	v_pk_add_f32 v[114:115], v[114:115], 1.0 op_sel_hi:[1,0]
	v_rcp_f32_e32 v110, v110
	v_rcp_f32_e32 v111, v111
	v_rcp_f32_e32 v114, v114
	v_rcp_f32_e32 v115, v115
	v_pk_mul_f32 v[104:105], v[104:105], v[110:111]
	s_nop 0
	v_pk_mul_f32 v[104:105], v[104:105], v[96:97]
	v_pk_mul_f32 v[96:97], v[106:107], v[114:115]
	s_nop 0
	v_pk_mul_f32 v[106:107], v[96:97], v[98:99]
	v_cvt_pk_bf16_f32 v96, v100, v101
	v_cvt_pk_bf16_f32 v97, v102, v103
	v_cvt_pk_bf16_f32 v98, v104, v105
	v_pk_mul_f32 v[100:101], v[94:95], s[16:17] op_sel_hi:[1,0]
	v_cvt_pk_bf16_f32 v99, v106, v107
	global_store_dwordx4 v[112:113], v[96:99], off
	v_exp_f32_e32 v100, v100
	v_exp_f32_e32 v101, v101
	v_pk_mul_f32 v[98:99], v[92:93], s[16:17] op_sel_hi:[1,0]
	v_or_b32_e32 v96, 32, v159
	v_exp_f32_e32 v98, v98
	v_exp_f32_e32 v99, v99
	v_pk_add_f32 v[100:101], v[100:101], 1.0 op_sel_hi:[1,0]
	v_mad_i64_i32 v[96:97], s[6:7], v96, s97, v[154:155]
	v_pk_add_f32 v[98:99], v[98:99], 1.0 op_sel_hi:[1,0]
	v_rcp_f32_e32 v100, v100
	v_rcp_f32_e32 v98, v98
	v_rcp_f32_e32 v99, v99
	v_rcp_f32_e32 v101, v101
	v_lshl_add_u64 v[96:97], v[96:97], 0, v[152:153]
	v_pk_mul_f32 v[92:93], v[92:93], v[98:99]
	s_nop 0
	v_pk_mul_f32 v[84:85], v[92:93], v[84:85]
	v_pk_mul_f32 v[92:93], v[94:95], v[100:101]
	v_pk_mul_f32 v[94:95], v[88:89], s[16:17] op_sel_hi:[1,0]
	v_pk_mul_f32 v[98:99], v[90:91], s[16:17] op_sel_hi:[1,0]
	v_exp_f32_e32 v94, v94
	v_exp_f32_e32 v95, v95
	v_exp_f32_e32 v98, v98
	v_exp_f32_e32 v99, v99
	v_pk_mul_f32 v[86:87], v[92:93], v[86:87]
	v_pk_add_f32 v[94:95], v[94:95], 1.0 op_sel_hi:[1,0]
	v_pk_add_f32 v[98:99], v[98:99], 1.0 op_sel_hi:[1,0]
	v_rcp_f32_e32 v94, v94
	v_rcp_f32_e32 v95, v95
	v_rcp_f32_e32 v98, v98
	v_rcp_f32_e32 v99, v99
	v_pk_mul_f32 v[88:89], v[88:89], v[94:95]
	s_nop 0
	v_pk_mul_f32 v[88:89], v[88:89], v[80:81]
	v_pk_mul_f32 v[80:81], v[90:91], v[98:99]
	s_nop 0
	v_pk_mul_f32 v[90:91], v[80:81], v[82:83]
	v_cvt_pk_bf16_f32 v80, v84, v85
	v_cvt_pk_bf16_f32 v81, v86, v87
	v_cvt_pk_bf16_f32 v82, v88, v89
	v_pk_mul_f32 v[84:85], v[78:79], s[16:17] op_sel_hi:[1,0]
	v_cvt_pk_bf16_f32 v83, v90, v91
	global_store_dwordx4 v[96:97], v[80:83], off
	v_exp_f32_e32 v84, v84
	v_exp_f32_e32 v85, v85
	v_pk_mul_f32 v[82:83], v[76:77], s[16:17] op_sel_hi:[1,0]
	v_or_b32_e32 v80, 48, v159
	v_exp_f32_e32 v82, v82
	v_exp_f32_e32 v83, v83
	v_pk_add_f32 v[84:85], v[84:85], 1.0 op_sel_hi:[1,0]
	v_mad_i64_i32 v[80:81], s[6:7], v80, s97, v[154:155]
	v_pk_add_f32 v[82:83], v[82:83], 1.0 op_sel_hi:[1,0]
	v_rcp_f32_e32 v84, v84
	v_rcp_f32_e32 v82, v82
	v_rcp_f32_e32 v83, v83
	v_rcp_f32_e32 v85, v85
	v_lshl_add_u64 v[80:81], v[80:81], 0, v[152:153]
	v_pk_mul_f32 v[76:77], v[76:77], v[82:83]
	s_nop 0
	v_pk_mul_f32 v[68:69], v[76:77], v[68:69]
; __device__ __forceinline__ unsigned cvt_pk_bf16(float lo, float hi) { unsigned r; asm volatile("v_cvt_pk_bf16_f32 %0, %1, %2" : "=v"(r) : "v"(lo), "v"(hi)); return r; }
; #define PG8_BAR __builtin_amdgcn_s_barrier()
;     __device__ __forceinline__ void operator()(const f32x4 (&acc)[2][2][4][2], const Unit& u, int wr, int wc, int fr, int fq) const {
;     ...
;             for (int m = 0; m < 4; ++m) {
;                 bf16_t* rowp = O + (size_t)(row0 + ai * HALF + m * 16) * ldc + col0;
;                 const f32x4 g0 = acc[ai][0][m][0], g1 = acc[ai][0][m][1], u0 = acc[ai][1][m][0], u1 = acc[ai][1][m][1];
;                 const f32x2 a = silu_mul_pk((f32x2){g0[0], g0[1]}, (f32x2){u0[0], u0[1]}), b = silu_mul_pk((f32x2){g0[2], g0[3]}, (f32x2){u0[2], u0[3]});
;                 const f32x2 c = silu_mul_pk((f32x2){g1[0], g1[1]}, (f32x2){u1[0], u1[1]}), d = silu_mul_pk((f32x2){g1[2], g1[3]}, (f32x2){u1[2], u1[3]});
;                 u32x4 w; w.x = cvt_pk_bf16(a.x, a.y); w.y = cvt_pk_bf16(b.x, b.y); w.z = cvt_pk_bf16(c.x, c.y); w.w = cvt_pk_bf16(d.x, d.y);
;                 *(u32x4*)rowp = w;
;             }
; template <class Epi, bool ALIGN_EPI, class Hook = NoHook>
; __device__ __forceinline__ void gemm_phase(LAS unsigned char* lds, const Gemm g, const StaticOrder& S, const Epi& E, const Hook& HK = Hook()) {
;     ...
;         E(acc, cur, wr, wc, fr, fq);
;         if (!has_next) break;
; #pragma unroll
;         for (int a = 0; a < 2; ++a)
; #pragma unroll
;             for (int b = 0; b < 2; ++b)
; #pragma unroll
;                 for (int m = 0; m < 4; ++m)
; #pragma unroll
;                     for (int n = 0; n < 2; ++n) acc[a][b][m][n] = (f32x4){0.f, 0.f, 0.f, 0.f};
;         cur = nxt; cA = nA; cB = nB; ++ui;
;         if constexpr (ALIGN_EPI) { if (wr == 1) PG8_BAR; }
	v_pk_mul_f32 v[76:77], v[78:79], v[84:85]
	v_pk_mul_f32 v[78:79], v[72:73], s[16:17] op_sel_hi:[1,0]
	v_pk_mul_f32 v[82:83], v[74:75], s[16:17] op_sel_hi:[1,0]
	v_exp_f32_e32 v78, v78
	v_exp_f32_e32 v79, v79
	v_exp_f32_e32 v82, v82
	v_exp_f32_e32 v83, v83
	v_pk_mul_f32 v[70:71], v[76:77], v[70:71]
	v_pk_add_f32 v[78:79], v[78:79], 1.0 op_sel_hi:[1,0]
	v_pk_add_f32 v[82:83], v[82:83], 1.0 op_sel_hi:[1,0]
	v_rcp_f32_e32 v78, v78
	v_rcp_f32_e32 v79, v79
	v_rcp_f32_e32 v82, v82
	v_rcp_f32_e32 v83, v83
	v_pk_mul_f32 v[72:73], v[72:73], v[78:79]
	s_nop 0
	v_pk_mul_f32 v[72:73], v[72:73], v[64:65]
	v_pk_mul_f32 v[64:65], v[74:75], v[82:83]
	s_nop 0
	v_pk_mul_f32 v[74:75], v[64:65], v[66:67]
	v_cvt_pk_bf16_f32 v64, v68, v69
	v_cvt_pk_bf16_f32 v65, v70, v71
	v_cvt_pk_bf16_f32 v66, v72, v73
	v_pk_mul_f32 v[68:69], v[62:63], s[16:17] op_sel_hi:[1,0]
	v_cvt_pk_bf16_f32 v67, v74, v75
	global_store_dwordx4 v[80:81], v[64:67], off
	v_exp_f32_e32 v68, v68
	v_exp_f32_e32 v69, v69
	v_pk_mul_f32 v[66:67], v[60:61], s[16:17] op_sel_hi:[1,0]
	v_add_u32_e32 v64, 0x80, v159
	v_exp_f32_e32 v66, v66
	v_exp_f32_e32 v67, v67
	v_pk_add_f32 v[68:69], v[68:69], 1.0 op_sel_hi:[1,0]
	v_mad_i64_i32 v[64:65], s[6:7], v64, s97, v[154:155]
	v_pk_add_f32 v[66:67], v[66:67], 1.0 op_sel_hi:[1,0]
	v_rcp_f32_e32 v68, v68
	v_rcp_f32_e32 v66, v66
	v_rcp_f32_e32 v67, v67
	v_rcp_f32_e32 v69, v69
	v_lshl_add_u64 v[64:65], v[64:65], 0, v[152:153]
	v_pk_mul_f32 v[60:61], v[60:61], v[66:67]
	s_nop 0
	v_pk_mul_f32 v[52:53], v[60:61], v[52:53]
	v_pk_mul_f32 v[60:61], v[62:63], v[68:69]
	v_pk_mul_f32 v[62:63], v[56:57], s[16:17] op_sel_hi:[1,0]
	v_pk_mul_f32 v[66:67], v[58:59], s[16:17] op_sel_hi:[1,0]
	v_exp_f32_e32 v62, v62
	v_exp_f32_e32 v63, v63
	v_exp_f32_e32 v66, v66
	v_exp_f32_e32 v67, v67
	v_pk_mul_f32 v[54:55], v[60:61], v[54:55]
	v_pk_add_f32 v[62:63], v[62:63], 1.0 op_sel_hi:[1,0]
	v_pk_add_f32 v[66:67], v[66:67], 1.0 op_sel_hi:[1,0]
	v_rcp_f32_e32 v62, v62
	v_rcp_f32_e32 v63, v63
	v_rcp_f32_e32 v66, v66
	v_rcp_f32_e32 v67, v67
	v_pk_mul_f32 v[56:57], v[56:57], v[62:63]
	s_nop 0
	v_pk_mul_f32 v[56:57], v[56:57], v[48:49]
	v_pk_mul_f32 v[48:49], v[58:59], v[66:67]
	s_nop 0
	v_pk_mul_f32 v[58:59], v[48:49], v[50:51]
	v_cvt_pk_bf16_f32 v48, v52, v53
	v_cvt_pk_bf16_f32 v49, v54, v55
	v_cvt_pk_bf16_f32 v50, v56, v57
	v_pk_mul_f32 v[52:53], v[46:47], s[16:17] op_sel_hi:[1,0]
	v_cvt_pk_bf16_f32 v51, v58, v59
	global_store_dwordx4 v[64:65], v[48:51], off
	v_exp_f32_e32 v52, v52
	v_exp_f32_e32 v53, v53
	v_pk_mul_f32 v[50:51], v[44:45], s[16:17] op_sel_hi:[1,0]
	v_add_u32_e32 v48, 0x90, v159
	v_exp_f32_e32 v50, v50
	v_exp_f32_e32 v51, v51
	v_pk_add_f32 v[52:53], v[52:53], 1.0 op_sel_hi:[1,0]
	v_mad_i64_i32 v[48:49], s[6:7], v48, s97, v[154:155]
	v_pk_add_f32 v[50:51], v[50:51], 1.0 op_sel_hi:[1,0]
	v_rcp_f32_e32 v52, v52
	v_rcp_f32_e32 v50, v50
	v_rcp_f32_e32 v51, v51
	v_rcp_f32_e32 v53, v53
	v_lshl_add_u64 v[48:49], v[48:49], 0, v[152:153]
	v_pk_mul_f32 v[44:45], v[44:45], v[50:51]
	s_nop 0
	v_pk_mul_f32 v[36:37], v[44:45], v[36:37]
	v_pk_mul_f32 v[44:45], v[46:47], v[52:53]
	v_pk_mul_f32 v[46:47], v[40:41], s[16:17] op_sel_hi:[1,0]
	v_pk_mul_f32 v[50:51], v[42:43], s[16:17] op_sel_hi:[1,0]
	v_exp_f32_e32 v46, v46
	v_exp_f32_e32 v47, v47
	v_exp_f32_e32 v50, v50
	v_exp_f32_e32 v51, v51
	v_pk_mul_f32 v[38:39], v[44:45], v[38:39]
	v_pk_add_f32 v[46:47], v[46:47], 1.0 op_sel_hi:[1,0]
	v_pk_add_f32 v[50:51], v[50:51], 1.0 op_sel_hi:[1,0]
	v_rcp_f32_e32 v46, v46
	v_rcp_f32_e32 v47, v47
	v_rcp_f32_e32 v50, v50
	v_rcp_f32_e32 v51, v51
	v_pk_mul_f32 v[40:41], v[40:41], v[46:47]
	s_nop 0
	v_pk_mul_f32 v[40:41], v[40:41], v[32:33]
	v_pk_mul_f32 v[32:33], v[42:43], v[50:51]
	s_nop 0
	v_pk_mul_f32 v[42:43], v[32:33], v[34:35]
	v_cvt_pk_bf16_f32 v32, v36, v37
	v_cvt_pk_bf16_f32 v33, v38, v39
	v_cvt_pk_bf16_f32 v34, v40, v41
	v_pk_mul_f32 v[36:37], v[30:31], s[16:17] op_sel_hi:[1,0]
	v_cvt_pk_bf16_f32 v35, v42, v43
	global_store_dwordx4 v[48:49], v[32:35], off
	v_exp_f32_e32 v36, v36
	v_exp_f32_e32 v37, v37
	v_pk_mul_f32 v[34:35], v[28:29], s[16:17] op_sel_hi:[1,0]
	v_add_u32_e32 v32, 0xa0, v159
	v_exp_f32_e32 v34, v34
	v_exp_f32_e32 v35, v35
	v_pk_add_f32 v[36:37], v[36:37], 1.0 op_sel_hi:[1,0]
	v_mad_i64_i32 v[32:33], s[6:7], v32, s97, v[154:155]
	v_pk_add_f32 v[34:35], v[34:35], 1.0 op_sel_hi:[1,0]
	v_rcp_f32_e32 v36, v36
	v_rcp_f32_e32 v34, v34
	v_rcp_f32_e32 v35, v35
	v_rcp_f32_e32 v37, v37
	v_lshl_add_u64 v[32:33], v[32:33], 0, v[152:153]
	v_pk_mul_f32 v[28:29], v[28:29], v[34:35]
	s_nop 0
	v_pk_mul_f32 v[20:21], v[28:29], v[20:21]
	v_pk_mul_f32 v[28:29], v[30:31], v[36:37]
	v_pk_mul_f32 v[30:31], v[24:25], s[16:17] op_sel_hi:[1,0]
	v_pk_mul_f32 v[34:35], v[26:27], s[16:17] op_sel_hi:[1,0]
	v_exp_f32_e32 v30, v30
	v_exp_f32_e32 v31, v31
	v_exp_f32_e32 v34, v34
	v_exp_f32_e32 v35, v35
	v_pk_mul_f32 v[22:23], v[28:29], v[22:23]
	v_pk_add_f32 v[30:31], v[30:31], 1.0 op_sel_hi:[1,0]
	v_pk_add_f32 v[34:35], v[34:35], 1.0 op_sel_hi:[1,0]
	v_rcp_f32_e32 v30, v30
	v_rcp_f32_e32 v31, v31
	v_rcp_f32_e32 v34, v34
	v_rcp_f32_e32 v35, v35
	v_pk_mul_f32 v[24:25], v[24:25], v[30:31]
	s_nop 0
	v_pk_mul_f32 v[24:25], v[24:25], v[16:17]
	v_pk_mul_f32 v[16:17], v[26:27], v[34:35]
	s_nop 0
	v_pk_mul_f32 v[26:27], v[16:17], v[18:19]
	v_cvt_pk_bf16_f32 v16, v20, v21
	v_cvt_pk_bf16_f32 v17, v22, v23
	v_cvt_pk_bf16_f32 v18, v24, v25
	v_pk_mul_f32 v[20:21], v[14:15], s[16:17] op_sel_hi:[1,0]
	v_cvt_pk_bf16_f32 v19, v26, v27
	global_store_dwordx4 v[32:33], v[16:19], off
	v_exp_f32_e32 v20, v20
	v_exp_f32_e32 v21, v21
	v_pk_mul_f32 v[18:19], v[12:13], s[16:17] op_sel_hi:[1,0]
	v_add_u32_e32 v16, 0xb0, v159
	v_exp_f32_e32 v18, v18
	v_exp_f32_e32 v19, v19
	v_pk_add_f32 v[20:21], v[20:21], 1.0 op_sel_hi:[1,0]
	v_mad_i64_i32 v[16:17], s[6:7], v16, s97, v[154:155]
	v_pk_add_f32 v[18:19], v[18:19], 1.0 op_sel_hi:[1,0]
	v_rcp_f32_e32 v20, v20
	v_rcp_f32_e32 v18, v18
	v_rcp_f32_e32 v19, v19
	v_rcp_f32_e32 v21, v21
	v_lshl_add_u64 v[16:17], v[16:17], 0, v[152:153]
	v_pk_mul_f32 v[12:13], v[12:13], v[18:19]
	s_nop 0
	v_pk_mul_f32 v[4:5], v[12:13], v[4:5]
	v_pk_mul_f32 v[12:13], v[14:15], v[20:21]
	v_pk_mul_f32 v[14:15], v[8:9], s[16:17] op_sel_hi:[1,0]
	v_pk_mul_f32 v[18:19], v[10:11], s[16:17] op_sel_hi:[1,0]
	v_exp_f32_e32 v14, v14
	v_exp_f32_e32 v15, v15
	v_exp_f32_e32 v18, v18
	v_exp_f32_e32 v19, v19
	v_pk_mul_f32 v[6:7], v[12:13], v[6:7]
	v_pk_add_f32 v[14:15], v[14:15], 1.0 op_sel_hi:[1,0]
	v_pk_add_f32 v[18:19], v[18:19], 1.0 op_sel_hi:[1,0]
	v_rcp_f32_e32 v14, v14
	v_rcp_f32_e32 v15, v15
	v_rcp_f32_e32 v18, v18
	v_rcp_f32_e32 v19, v19
	v_pk_mul_f32 v[8:9], v[8:9], v[14:15]
	s_nop 0
	v_pk_mul_f32 v[8:9], v[8:9], v[0:1]
	v_pk_mul_f32 v[0:1], v[10:11], v[18:19]
	s_nop 0
	v_pk_mul_f32 v[10:11], v[0:1], v[2:3]
	v_cvt_pk_bf16_f32 v0, v4, v5
	v_cvt_pk_bf16_f32 v1, v6, v7
	v_cvt_pk_bf16_f32 v2, v8, v9
	s_nop 0
	v_cvt_pk_bf16_f32 v3, v10, v11
	global_store_dwordx4 v[16:17], v[0:3], off
	s_cbranch_vccnz .LBB0_44
	s_andn2_b64 vcc, exec, s[4:5]
	s_cbranch_vccnz .LBB0_43
	s_branch .LBB0_43
; #define PG8_WAIT_V(n) asm volatile("s_waitcnt vmcnt(" #n ")" ::: "memory")
; #define PG8_BAR __builtin_amdgcn_s_barrier()
; template <class Epi, bool ALIGN_EPI, class Hook = NoHook>
; __device__ __forceinline__ void gemm_phase(LAS unsigned char* lds, const Gemm g, const StaticOrder& S, const Epi& E, const Hook& HK = Hook()) {
;     ...
;     PG8_WAIT_V(0);
;     if constexpr (!ALIGN_EPI) { if (wr == 0) PG8_BAR; }
;     PG8_BAR;
.LBB0_54:
	s_cmp_lg_u64 s[14:15], 0
	s_cbranch_scc0 .Lnoalign_skip_P1
	s_barrier

; __device__ __forceinline__ unsigned cvt_pk_bf16(float lo, float hi) { unsigned r; asm volatile("v_cvt_pk_bf16_f32 %0, %1, %2" : "=v"(r) : "v"(lo), "v"(hi)); return r; }
;     __device__ __forceinline__ void operator()(const f32x4 (&acc)[2][2][4][2], const Unit& u, int wr, int wc, int fr, int fq) const {
;         const int row0 = u.pm * BM + wr * 64 + fr; const int col0 = u.pn * BM + wc * 32 + 8 * fq;
; #pragma unroll
;         for (int ai = 0; ai < 2; ++ai) {
;             f32x4 p0[4][2], p1[4][2];
; #pragma unroll
;             for (int m = 0; m < 4; ++m)
; #pragma unroll
;                 for (int bj = 0; bj < 2; ++bj) {
;                     const size_t e = (size_t)(row0 + ai * HALF + m * 16) * 2048 + col0 + bj * HALF;
;                     if (IN_F32) { p0[m][bj] = *(const f32x4*)((const float*)base + e); p1[m][bj] = *(const f32x4*)((const float*)base + e + 4); }
;                     else { const u32x4 w = *(const u32x4*)((const bf16_t*)base + e); p0[m][bj] = (f32x4){bflo(w.x), bfhi(w.x), bflo(w.y), bfhi(w.y)}; p1[m][bj] = (f32x4){bflo(w.z), bfhi(w.z), bflo(w.w), bfhi(w.w)}; }
;                 }
; #pragma unroll
;             for (int m = 0; m < 4; ++m)
; #pragma unroll
;                 for (int bj = 0; bj < 2; ++bj) {
;                     const size_t e = (size_t)(row0 + ai * HALF + m * 16) * 2048 + col0 + bj * HALF;
;                     const f32x4 v0 = p0[m][bj] + acc[ai][bj][m][0] * scale, v1 = p1[m][bj] + acc[ai][bj][m][1] * scale;
;                     if (OUT_F32) { *(f32x4*)((float*)out + e) = v0; *(f32x4*)((float*)out + e + 4) = v1; }
;                     else { u32x4 w; w.x = cvt_pk_bf16(v0[0], v0[1]); w.y = cvt_pk_bf16(v0[2], v0[3]); w.z = cvt_pk_bf16(v1[0], v1[1]); w.w = cvt_pk_bf16(v1[2], v1[3]); *(u32x4*)((bf16_t*)out + e) = w; }
;                 }
.LBB0_131:
	v_lshl_add_u32 v164, s92, 8, v137
	v_lshl_or_b32 v160, s93, 8, v143
	v_ashrrev_i32_e32 v161, 31, v160
	v_ashrrev_i32_e32 v165, 31, v164
	v_lshl_add_u64 v[162:163], v[160:161], 2, s[8:9]
	v_lshlrev_b64 v[128:129], 13, v[164:165]
	v_or_b32_e32 v198, 16, v164
	v_lshl_add_u64 v[128:129], v[162:163], 0, v[128:129]
	v_ashrrev_i32_e32 v199, 31, v198
	global_load_dwordx4 v[170:173], v[128:129], off
	global_load_dwordx4 v[174:177], v[128:129], off offset:16
	global_load_dwordx4 v[178:181], v[128:129], off offset:512
	global_load_dwordx4 v[182:185], v[128:129], off offset:528
	v_lshlrev_b64 v[128:129], 13, v[198:199]
	v_or_b32_e32 v232, 32, v164
	v_lshl_add_u64 v[128:129], v[162:163], 0, v[128:129]
	v_ashrrev_i32_e32 v233, 31, v232
	global_load_dwordx4 v[186:189], v[128:129], off
	global_load_dwordx4 v[190:193], v[128:129], off offset:16
	global_load_dwordx4 v[194:197], v[128:129], off offset:528
	global_load_dwordx4 v[204:207], v[128:129], off offset:512
	v_lshlrev_b64 v[128:129], 13, v[232:233]
	v_lshl_add_u64 v[128:129], v[162:163], 0, v[128:129]
	global_load_dwordx4 v[208:211], v[128:129], off
	global_load_dwordx4 v[212:215], v[128:129], off offset:16
	global_load_dwordx4 v[216:219], v[128:129], off offset:512
	global_load_dwordx4 v[220:223], v[128:129], off offset:528
	v_or_b32_e32 v234, 48, v164
	v_ashrrev_i32_e32 v235, 31, v234
	v_lshlrev_b64 v[128:129], 13, v[234:235]
	v_lshl_add_u64 v[128:129], v[162:163], 0, v[128:129]
	global_load_dwordx4 v[224:227], v[128:129], off
	global_load_dwordx4 v[228:231], v[128:129], off offset:16
	global_load_dwordx4 v[132:135], v[128:129], off offset:512
	s_nop 0
	global_load_dwordx4 v[128:131], v[128:129], off offset:528
	v_lshlrev_b64 v[236:237], 12, v[164:165]
	v_lshlrev_b64 v[160:161], 1, v[160:161]
	v_lshl_add_u64 v[236:237], s[60:61], 0, v[236:237]
	v_lshlrev_b64 v[198:199], 12, v[198:199]
	v_lshl_add_u64 v[236:237], v[236:237], 0, v[160:161]
	v_lshl_add_u64 v[198:199], s[60:61], 0, v[198:199]
	v_lshlrev_b64 v[232:233], 12, v[232:233]
	v_lshl_add_u64 v[198:199], v[198:199], 0, v[160:161]
	v_lshl_add_u64 v[232:233], s[60:61], 0, v[232:233]
	v_lshl_add_u64 v[232:233], v[232:233], 0, v[160:161]
	s_and_b64 vcc, exec, s[0:1]
	s_mov_b64 s[0:1], -1
	s_waitcnt vmcnt(0)
	v_pk_fma_f32 v[126:127], v[126:127], 0.5, v[172:173] op_sel_hi:[1,0,1]
	v_pk_fma_f32 v[122:123], v[122:123], 0.5, v[176:177] op_sel_hi:[1,0,1]
	v_pk_fma_f32 v[124:125], v[124:125], 0.5, v[170:171] op_sel_hi:[1,0,1]
	v_pk_fma_f32 v[120:121], v[120:121], 0.5, v[174:175] op_sel_hi:[1,0,1]
	v_pk_fma_f32 v[106:107], v[106:107], 0.5, v[180:181] op_sel_hi:[1,0,1]
	v_pk_fma_f32 v[104:105], v[104:105], 0.5, v[178:179] op_sel_hi:[1,0,1]
	v_pk_fma_f32 v[170:171], v[98:99], 0.5, v[184:185] op_sel_hi:[1,0,1]
	v_pk_fma_f32 v[172:173], v[96:97], 0.5, v[182:183] op_sel_hi:[1,0,1]
	v_cvt_pk_bf16_f32 v96, v124, v125
	v_cvt_pk_bf16_f32 v97, v126, v127
	v_cvt_pk_bf16_f32 v98, v120, v121
	v_cvt_pk_bf16_f32 v99, v122, v123
	v_pk_fma_f32 v[122:123], v[86:87], 0.5, v[218:219] op_sel_hi:[1,0,1]
	global_store_dwordx4 v[236:237], v[96:99], off
	v_cvt_pk_bf16_f32 v86, v104, v105
	v_cvt_pk_bf16_f32 v87, v106, v107
	v_pk_fma_f32 v[118:119], v[118:119], 0.5, v[188:189] op_sel_hi:[1,0,1]
	v_pk_fma_f32 v[116:117], v[116:117], 0.5, v[186:187] op_sel_hi:[1,0,1]
	v_pk_fma_f32 v[120:121], v[88:89], 0.5, v[194:195] op_sel_hi:[1,0,1]
	v_cvt_pk_bf16_f32 v88, v172, v173
	v_cvt_pk_bf16_f32 v89, v170, v171
	global_store_dwordx4 v[236:237], v[86:89], off offset:256
	v_pk_fma_f32 v[114:115], v[114:115], 0.5, v[192:193] op_sel_hi:[1,0,1]
	v_pk_fma_f32 v[112:113], v[112:113], 0.5, v[190:191] op_sel_hi:[1,0,1]
	v_cvt_pk_bf16_f32 v86, v116, v117
	v_cvt_pk_bf16_f32 v87, v118, v119
	v_pk_fma_f32 v[94:95], v[94:95], 0.5, v[206:207] op_sel_hi:[1,0,1]
	v_pk_fma_f32 v[92:93], v[92:93], 0.5, v[204:205] op_sel_hi:[1,0,1]
	v_cvt_pk_bf16_f32 v88, v112, v113
	v_cvt_pk_bf16_f32 v89, v114, v115
	global_store_dwordx4 v[198:199], v[86:89], off
	v_pk_fma_f32 v[90:91], v[90:91], 0.5, v[196:197] op_sel_hi:[1,0,1]
	v_pk_fma_f32 v[110:111], v[110:111], 0.5, v[210:211] op_sel_hi:[1,0,1]
	v_cvt_pk_bf16_f32 v86, v92, v93
	v_cvt_pk_bf16_f32 v87, v94, v95
	v_pk_fma_f32 v[108:109], v[108:109], 0.5, v[208:209] op_sel_hi:[1,0,1]
	v_cvt_pk_bf16_f32 v88, v120, v121
	v_cvt_pk_bf16_f32 v89, v90, v91
	global_store_dwordx4 v[198:199], v[86:89], off offset:256
	v_pk_fma_f32 v[102:103], v[102:103], 0.5, v[214:215] op_sel_hi:[1,0,1]
	v_pk_fma_f32 v[100:101], v[100:101], 0.5, v[212:213] op_sel_hi:[1,0,1]
	v_cvt_pk_bf16_f32 v86, v108, v109
	v_cvt_pk_bf16_f32 v87, v110, v111
	v_pk_fma_f32 v[84:85], v[84:85], 0.5, v[216:217] op_sel_hi:[1,0,1]
	v_cvt_pk_bf16_f32 v88, v100, v101
	v_cvt_pk_bf16_f32 v89, v102, v103
	global_store_dwordx4 v[232:233], v[86:89], off
	v_pk_fma_f32 v[80:81], v[80:81], 0.5, v[224:225] op_sel_hi:[1,0,1]
	v_pk_fma_f32 v[70:71], v[70:71], 0.5, v[134:135] op_sel_hi:[1,0,1]
	v_pk_fma_f32 v[86:87], v[78:79], 0.5, v[222:223] op_sel_hi:[1,0,1]
	v_pk_fma_f32 v[78:79], v[76:77], 0.5, v[220:221] op_sel_hi:[1,0,1]
	v_cvt_pk_bf16_f32 v76, v84, v85
	v_cvt_pk_bf16_f32 v77, v122, v123
	v_pk_fma_f32 v[68:69], v[68:69], 0.5, v[132:133] op_sel_hi:[1,0,1]
	v_cvt_pk_bf16_f32 v78, v78, v79
	v_cvt_pk_bf16_f32 v79, v86, v87
	global_store_dwordx4 v[232:233], v[76:79], off offset:256
	v_add_u32_e32 v132, 0xa0, v164
	v_ashrrev_i32_e32 v133, 31, v132
	v_lshlrev_b64 v[76:77], 12, v[234:235]
	v_lshl_add_u64 v[76:77], s[60:61], 0, v[76:77]
	v_pk_fma_f32 v[78:79], v[82:83], 0.5, v[226:227] op_sel_hi:[1,0,1]
	v_pk_fma_f32 v[82:83], v[74:75], 0.5, v[230:231] op_sel_hi:[1,0,1]
	v_pk_fma_f32 v[74:75], v[72:73], 0.5, v[228:229] op_sel_hi:[1,0,1]
; #define PG8_WAIT_V(n) asm volatile("s_waitcnt vmcnt(" #n ")" ::: "memory")
; #define PG8_BAR __builtin_amdgcn_s_barrier()
;     __device__ __forceinline__ void operator()(const f32x4 (&acc)[2][2][4][2], const Unit& u, int wr, int wc, int fr, int fq) const {
;     ...
;         for (int ai = 0; ai < 2; ++ai) {
;             f32x4 p0[4][2], p1[4][2];
; #pragma unroll
;             for (int m = 0; m < 4; ++m)
; #pragma unroll
;                 for (int bj = 0; bj < 2; ++bj) {
;                     const size_t e = (size_t)(row0 + ai * HALF + m * 16) * 2048 + col0 + bj * HALF;
;                     if (IN_F32) { p0[m][bj] = *(const f32x4*)((const float*)base + e); p1[m][bj] = *(const f32x4*)((const float*)base + e + 4); }
;                     else { const u32x4 w = *(const u32x4*)((const bf16_t*)base + e); p0[m][bj] = (f32x4){bflo(w.x), bfhi(w.x), bflo(w.y), bfhi(w.y)}; p1[m][bj] = (f32x4){bflo(w.z), bfhi(w.z), bflo(w.w), bfhi(w.w)}; }
;                 }
; #pragma unroll
;             for (int m = 0; m < 4; ++m)
; #pragma unroll
;                 for (int bj = 0; bj < 2; ++bj) {
;                     const size_t e = (size_t)(row0 + ai * HALF + m * 16) * 2048 + col0 + bj * HALF;
;                     const f32x4 v0 = p0[m][bj] + acc[ai][bj][m][0] * scale, v1 = p1[m][bj] + acc[ai][bj][m][1] * scale;
;                     if (OUT_F32) { *(f32x4*)((float*)out + e) = v0; *(f32x4*)((float*)out + e + 4) = v1; }
;                     else { u32x4 w; w.x = cvt_pk_bf16(v0[0], v0[1]); w.y = cvt_pk_bf16(v0[2], v0[3]); w.z = cvt_pk_bf16(v1[0], v1[1]); w.w = cvt_pk_bf16(v1[2], v1[3]); *(u32x4*)((bf16_t*)out + e) = w; }
;                 }
; template <class Epi, bool ALIGN_EPI, class Hook = NoHook>
; __device__ __forceinline__ void gemm_phase(LAS unsigned char* lds, const Gemm g, const StaticOrder& S, const Epi& E, const Hook& HK = Hook()) {
;     ...
;         if (!has_next) break;
; #pragma unroll
;         for (int a = 0; a < 2; ++a)
; #pragma unroll
;             for (int b = 0; b < 2; ++b)
; #pragma unroll
;                 for (int m = 0; m < 4; ++m)
; #pragma unroll
;                     for (int n = 0; n < 2; ++n) acc[a][b][m][n] = (f32x4){0.f, 0.f, 0.f, 0.f};
;         cur = nxt; cA = nA; cB = nB; ++ui;
;         if constexpr (ALIGN_EPI) { if (wr == 1) PG8_BAR; }
;     }
;     PG8_WAIT_V(0);
;     if constexpr (!ALIGN_EPI) { if (wr == 0) PG8_BAR; }
;     PG8_BAR;
	v_cvt_pk_bf16_f32 v72, v80, v81
	v_cvt_pk_bf16_f32 v73, v78, v79
	v_lshl_add_u64 v[76:77], v[76:77], 0, v[160:161]
	v_cvt_pk_bf16_f32 v74, v74, v75
	v_cvt_pk_bf16_f32 v75, v82, v83
	global_store_dwordx4 v[76:77], v[72:75], off
	v_lshlrev_b64 v[96:97], 13, v[132:133]
	v_lshl_add_u64 v[108:109], v[162:163], 0, v[96:97]
	v_pk_fma_f32 v[72:73], v[66:67], 0.5, v[130:131] op_sel_hi:[1,0,1]
	v_pk_fma_f32 v[66:67], v[64:65], 0.5, v[128:129] op_sel_hi:[1,0,1]
	v_add_u32_e32 v128, 0x80, v164
	v_cvt_pk_bf16_f32 v64, v68, v69
	v_cvt_pk_bf16_f32 v65, v70, v71
	v_ashrrev_i32_e32 v129, 31, v128
	v_cvt_pk_bf16_f32 v66, v66, v67
	v_cvt_pk_bf16_f32 v67, v72, v73
	global_store_dwordx4 v[76:77], v[64:67], off offset:256
	v_add_u32_e32 v130, 0x90, v164
	v_ashrrev_i32_e32 v131, 31, v130
	v_lshlrev_b64 v[64:65], 13, v[128:129]
	v_lshl_add_u64 v[76:77], v[162:163], 0, v[64:65]
	global_load_dwordx4 v[64:67], v[76:77], off
	global_load_dwordx4 v[68:71], v[76:77], off offset:16
	global_load_dwordx4 v[72:75], v[76:77], off offset:528
	s_nop 0
	global_load_dwordx4 v[76:79], v[76:77], off offset:512
	v_lshlrev_b64 v[80:81], 13, v[130:131]
	v_lshl_add_u64 v[92:93], v[162:163], 0, v[80:81]
	global_load_dwordx4 v[80:83], v[92:93], off
	global_load_dwordx4 v[84:87], v[92:93], off offset:16
	global_load_dwordx4 v[88:91], v[92:93], off offset:512
	s_nop 0
	global_load_dwordx4 v[92:95], v[92:93], off offset:528
	s_nop 0
	global_load_dwordx4 v[96:99], v[108:109], off
	global_load_dwordx4 v[100:103], v[108:109], off offset:16
	global_load_dwordx4 v[104:107], v[108:109], off offset:512
	s_nop 0
	global_load_dwordx4 v[108:111], v[108:109], off offset:528
	v_add_u32_e32 v134, 0xb0, v164
	v_ashrrev_i32_e32 v135, 31, v134
	v_lshlrev_b64 v[112:113], 13, v[134:135]
	v_lshl_add_u64 v[124:125], v[162:163], 0, v[112:113]
	global_load_dwordx4 v[112:115], v[124:125], off
	global_load_dwordx4 v[116:119], v[124:125], off offset:16
	global_load_dwordx4 v[120:123], v[124:125], off offset:512
	s_nop 0
	global_load_dwordx4 v[124:127], v[124:125], off offset:528
	v_lshlrev_b64 v[128:129], 12, v[128:129]
	v_lshl_add_u64 v[128:129], s[60:61], 0, v[128:129]
	v_lshlrev_b64 v[130:131], 12, v[130:131]
	v_lshl_add_u64 v[128:129], v[128:129], 0, v[160:161]
	s_waitcnt vmcnt(15)
	v_pk_fma_f32 v[62:63], v[62:63], 0.5, v[66:67] op_sel_hi:[1,0,1]
	v_pk_fma_f32 v[60:61], v[60:61], 0.5, v[64:65] op_sel_hi:[1,0,1]
	s_waitcnt vmcnt(13)
	v_pk_fma_f32 v[66:67], v[40:41], 0.5, v[72:73] op_sel_hi:[1,0,1]
	s_waitcnt vmcnt(12)
	v_pk_fma_f32 v[44:45], v[44:45], 0.5, v[76:77] op_sel_hi:[1,0,1]
	v_cvt_pk_bf16_f32 v40, v60, v61
	v_cvt_pk_bf16_f32 v41, v62, v63
	v_pk_fma_f32 v[58:59], v[58:59], 0.5, v[70:71] op_sel_hi:[1,0,1]
	v_pk_fma_f32 v[56:57], v[56:57], 0.5, v[68:69] op_sel_hi:[1,0,1]
	v_pk_fma_f32 v[46:47], v[46:47], 0.5, v[78:79] op_sel_hi:[1,0,1]
	v_pk_fma_f32 v[64:65], v[42:43], 0.5, v[74:75] op_sel_hi:[1,0,1]
	v_cvt_pk_bf16_f32 v42, v56, v57
	v_cvt_pk_bf16_f32 v43, v58, v59
	global_store_dwordx4 v[128:129], v[40:43], off
	s_waitcnt vmcnt(12)
	v_pk_fma_f32 v[54:55], v[54:55], 0.5, v[82:83] op_sel_hi:[1,0,1]
	v_pk_fma_f32 v[52:53], v[52:53], 0.5, v[80:81] op_sel_hi:[1,0,1]
	v_cvt_pk_bf16_f32 v40, v44, v45
	v_cvt_pk_bf16_f32 v41, v46, v47
	v_lshl_add_u64 v[44:45], s[60:61], 0, v[130:131]
	v_cvt_pk_bf16_f32 v42, v66, v67
	v_cvt_pk_bf16_f32 v43, v64, v65
	global_store_dwordx4 v[128:129], v[40:43], off offset:256
	v_lshl_add_u64 v[44:45], v[44:45], 0, v[160:161]
	s_waitcnt vmcnt(12)
	v_pk_fma_f32 v[50:51], v[50:51], 0.5, v[86:87] op_sel_hi:[1,0,1]
	v_cvt_pk_bf16_f32 v40, v52, v53
	v_cvt_pk_bf16_f32 v41, v54, v55
	v_pk_fma_f32 v[48:49], v[48:49], 0.5, v[84:85] op_sel_hi:[1,0,1]
	s_waitcnt vmcnt(11)
	v_pk_fma_f32 v[38:39], v[38:39], 0.5, v[90:91] op_sel_hi:[1,0,1]
	v_cvt_pk_bf16_f32 v42, v48, v49
	v_cvt_pk_bf16_f32 v43, v50, v51
	global_store_dwordx4 v[44:45], v[40:43], off
	v_pk_fma_f32 v[36:37], v[36:37], 0.5, v[88:89] op_sel_hi:[1,0,1]
	s_waitcnt vmcnt(10)
	v_pk_fma_f32 v[32:33], v[32:33], 0.5, v[96:97] op_sel_hi:[1,0,1]
	v_pk_fma_f32 v[40:41], v[30:31], 0.5, v[94:95] op_sel_hi:[1,0,1]
	v_pk_fma_f32 v[30:31], v[28:29], 0.5, v[92:93] op_sel_hi:[1,0,1]
	v_cvt_pk_bf16_f32 v28, v36, v37
	v_cvt_pk_bf16_f32 v29, v38, v39
	s_waitcnt vmcnt(8)
	v_pk_fma_f32 v[22:23], v[22:23], 0.5, v[106:107] op_sel_hi:[1,0,1]
	v_cvt_pk_bf16_f32 v30, v30, v31
	v_cvt_pk_bf16_f32 v31, v40, v41
	global_store_dwordx4 v[44:45], v[28:31], off offset:256
	v_pk_fma_f32 v[20:21], v[20:21], 0.5, v[104:105] op_sel_hi:[1,0,1]
	s_waitcnt vmcnt(7)
	v_pk_fma_f32 v[16:17], v[16:17], 0.5, v[112:113] op_sel_hi:[1,0,1]
	v_lshlrev_b64 v[28:29], 12, v[132:133]
	v_lshl_add_u64 v[28:29], s[60:61], 0, v[28:29]
	v_pk_fma_f32 v[30:31], v[34:35], 0.5, v[98:99] op_sel_hi:[1,0,1]
	v_pk_fma_f32 v[34:35], v[26:27], 0.5, v[102:103] op_sel_hi:[1,0,1]
	v_pk_fma_f32 v[26:27], v[24:25], 0.5, v[100:101] op_sel_hi:[1,0,1]
	v_cvt_pk_bf16_f32 v24, v32, v33
	v_cvt_pk_bf16_f32 v25, v30, v31
	v_lshl_add_u64 v[28:29], v[28:29], 0, v[160:161]
	v_cvt_pk_bf16_f32 v26, v26, v27
	v_cvt_pk_bf16_f32 v27, v34, v35
	global_store_dwordx4 v[28:29], v[24:27], off
	s_waitcnt vmcnt(6)
	v_pk_fma_f32 v[6:7], v[6:7], 0.5, v[122:123] op_sel_hi:[1,0,1]
	v_pk_fma_f32 v[4:5], v[4:5], 0.5, v[120:121] op_sel_hi:[1,0,1]
	v_pk_fma_f32 v[24:25], v[14:15], 0.5, v[110:111] op_sel_hi:[1,0,1]
	v_pk_fma_f32 v[14:15], v[12:13], 0.5, v[108:109] op_sel_hi:[1,0,1]
	v_cvt_pk_bf16_f32 v12, v20, v21
	v_cvt_pk_bf16_f32 v13, v22, v23
	s_nop 0
	v_cvt_pk_bf16_f32 v14, v14, v15
	v_cvt_pk_bf16_f32 v15, v24, v25
	global_store_dwordx4 v[28:29], v[12:15], off offset:256
	s_nop 1
	v_lshlrev_b64 v[12:13], 12, v[134:135]
	v_lshl_add_u64 v[12:13], s[60:61], 0, v[12:13]
	v_pk_fma_f32 v[14:15], v[18:19], 0.5, v[114:115] op_sel_hi:[1,0,1]
	v_pk_fma_f32 v[18:19], v[10:11], 0.5, v[118:119] op_sel_hi:[1,0,1]
	v_pk_fma_f32 v[10:11], v[8:9], 0.5, v[116:117] op_sel_hi:[1,0,1]
	v_cvt_pk_bf16_f32 v8, v16, v17
	v_cvt_pk_bf16_f32 v9, v14, v15
	v_lshl_add_u64 v[12:13], v[12:13], 0, v[160:161]
	v_cvt_pk_bf16_f32 v10, v10, v11
	v_cvt_pk_bf16_f32 v11, v18, v19
	global_store_dwordx4 v[12:13], v[8:11], off
	s_waitcnt vmcnt(7)
	s_nop 0
	v_pk_fma_f32 v[8:9], v[2:3], 0.5, v[126:127] op_sel_hi:[1,0,1]
	v_pk_fma_f32 v[2:3], v[0:1], 0.5, v[124:125] op_sel_hi:[1,0,1]
	v_cvt_pk_bf16_f32 v0, v4, v5
	v_cvt_pk_bf16_f32 v1, v6, v7
	s_nop 0
	v_cvt_pk_bf16_f32 v2, v2, v3
	v_cvt_pk_bf16_f32 v3, v8, v9
	global_store_dwordx4 v[12:13], v[0:3], off offset:256
	s_cbranch_vccnz .LBB0_116
	s_andn2_b64 vcc, exec, s[12:13]
	s_cbranch_vccnz .LBB0_115
	s_branch .LBB0_115
.LBB0_134:
	s_cmp_lg_u64 s[16:17], 0
	s_cbranch_scc0 .Lnoalign_skip_P2
	s_barrier

; #define PG8_STAGE(bufoff, gbase, voff) do { _Pragma("unroll") for (int _i = 0; _i < 2; ++_i) \
;         __builtin_amdgcn_global_load_lds((const unsigned*)((const char*)(gbase) + (voff)[_i]), (LAS unsigned*)(lds + (bufoff) + ldsw + _i * 8192), 16, 0, 0); } while (0)
; #define PG8_LDA(dst, b, h) do { _Pragma("unroll") for (int m = 0; m < 4; ++m) _Pragma("unroll") for (int k = 0; k < 2; ++k) dst[m][k] = *(const LAS bf16x8*)(lds + PG8_SA(b, h) + aoff + m * 2048 + k * 1024); } while (0)
; #define PG8_LDB(dst, b, h) do { _Pragma("unroll") for (int n = 0; n < 2; ++n) _Pragma("unroll") for (int k = 0; k < 2; ++k) dst[n][k] = *(const LAS bf16x8*)(lds + PG8_SB(b, h) + boff + n * 2048 + k * 1024); } while (0)
; #define PG8_MMA(ai, bj, At, Bt) do { __builtin_amdgcn_s_setprio(1); _Pragma("unroll") for (int m = 0; m < 4; ++m) _Pragma("unroll") for (int n = 0; n < 2; ++n) _Pragma("unroll") for (int k = 0; k < 2; ++k) \
;         acc[ai][bj][m][n] = __builtin_amdgcn_mfma_f32_16x16x32_bf16(Bt[n][k], At[m][k], acc[ai][bj][m][n], 0, 0, 0); __builtin_amdgcn_s_setprio(0); } while (0)
; #define PG8_WAIT_V(n) asm volatile("s_waitcnt vmcnt(" #n ")" ::: "memory")
; #define PG8_WAIT_L(n) asm volatile("s_waitcnt lgkmcnt(" #n ")" ::: "memory")
; #define PG8_BAR __builtin_amdgcn_s_barrier()
; #define PG8_SCHED __builtin_amdgcn_sched_barrier(0)
; template <class Epi, bool ALIGN_EPI, class Hook = NoHook>
; __device__ __forceinline__ void gemm_phase(LAS unsigned char* lds, const Gemm g, const StaticOrder& S, const Epi& E, const Hook& HK = Hook()) {
;     ...
;             PG8_LDB(B0, 0, 0); PG8_LDB(B1, 0, 1); PG8_SCHED; PG8_LDA(At, 0, 0); PG8_STAGE(PG8_SA(1, 1), a1 + hstepA, voffA);
;             PG8_WAIT_V(8); PG8_WAIT_L(0); PG8_BAR; PG8_MMA(0, 0, At, B0); PG8_MMA(0, 1, At, B1); PG8_BAR; PG8_SCHED;
;             PG8_LDA(At, 0, 1); PG8_STAGE(PG8_SB(0, 0), b2, voffB); PG8_STAGE(PG8_SB(0, 1), b2 + hstepB, voffB); PG8_STAGE(PG8_SA(0, 0), a2, voffA);
;             PG8_WAIT_V(8); PG8_WAIT_L(0); PG8_BAR; PG8_MMA(1, 0, At, B0); PG8_MMA(1, 1, At, B1); PG8_BAR; PG8_SCHED;
.LBB0_270:
	ds_read_b128 v[156:159], v141
	ds_read_b128 v[160:163], v141 offset:1024
	ds_read_b128 v[168:171], v141 offset:2048
	ds_read_b128 v[172:175], v141 offset:3072
	ds_read_b128 v[176:179], v143
	ds_read_b128 v[180:183], v143 offset:1024
	ds_read_b128 v[184:187], v143 offset:2048
	ds_read_b128 v[188:191], v143 offset:3072
	s_add_u32 s34, s86, 0xfff80080
	s_addc_u32 s35, s87, -1
	s_cmp_eq_u32 s51, 28
	s_cselect_b32 s91, s5, s35
	s_cselect_b32 s90, s19, s34
	s_cselect_b32 s89, s21, s50
	s_cselect_b32 s88, s26, s27
	v_lshl_add_u64 v[164:165], s[86:87], 0, v[148:149]
	s_add_i32 m0, s28, 0xc000
	ds_read_b128 v[192:195], v167
	ds_read_b128 v[196:199], v167 offset:1024
	ds_read_b128 v[204:207], v167 offset:2048
	ds_read_b128 v[208:211], v167 offset:3072
	ds_read_b128 v[212:215], v167 offset:4096
	ds_read_b128 v[216:219], v167 offset:5120
	ds_read_b128 v[220:223], v167 offset:6144
	ds_read_b128 v[224:227], v167 offset:7168
	global_load_lds_dwordx4 v[164:165], off
	v_lshl_add_u64 v[164:165], s[86:87], 0, v[150:151]
	s_add_i32 m0, s28, 0xe000
	s_nop 0
	global_load_lds_dwordx4 v[164:165], off
	s_waitcnt vmcnt(8)
	s_waitcnt lgkmcnt(0)
	s_barrier
	s_waitcnt lgkmcnt(0)
	v_mfma_f32_16x16x32_bf16 v[124:127], v[156:159], v[192:195], v[124:127]
	v_mfma_f32_16x16x32_bf16 v[120:123], v[168:171], v[192:195], v[120:123]
	v_mfma_f32_16x16x32_bf16 v[108:111], v[156:159], v[204:207], v[108:111]
	v_mfma_f32_16x16x32_bf16 v[104:107], v[168:171], v[204:207], v[104:107]
	v_mfma_f32_16x16x32_bf16 v[92:95], v[156:159], v[212:215], v[92:95]
	v_mfma_f32_16x16x32_bf16 v[88:91], v[168:171], v[212:215], v[88:91]
	v_mfma_f32_16x16x32_bf16 v[76:79], v[156:159], v[220:223], v[76:79]
	v_mfma_f32_16x16x32_bf16 v[72:75], v[168:171], v[220:223], v[72:75]
	v_mfma_f32_16x16x32_bf16 v[124:127], v[160:163], v[196:199], v[124:127]
	v_mfma_f32_16x16x32_bf16 v[120:123], v[172:175], v[196:199], v[120:123]
	v_mfma_f32_16x16x32_bf16 v[108:111], v[160:163], v[208:211], v[108:111]
	v_mfma_f32_16x16x32_bf16 v[104:107], v[172:175], v[208:211], v[104:107]
	v_mfma_f32_16x16x32_bf16 v[92:95], v[160:163], v[216:219], v[92:95]
	v_mfma_f32_16x16x32_bf16 v[88:91], v[172:175], v[216:219], v[88:91]
	v_mfma_f32_16x16x32_bf16 v[76:79], v[160:163], v[224:227], v[76:79]
	v_mfma_f32_16x16x32_bf16 v[72:75], v[172:175], v[224:227], v[72:75]
	v_mfma_f32_16x16x32_bf16 v[116:119], v[176:179], v[192:195], v[116:119]
	v_mfma_f32_16x16x32_bf16 v[112:115], v[184:187], v[192:195], v[112:115]
	v_mfma_f32_16x16x32_bf16 v[100:103], v[176:179], v[204:207], v[100:103]
	v_mfma_f32_16x16x32_bf16 v[96:99], v[184:187], v[204:207], v[96:99]
	v_mfma_f32_16x16x32_bf16 v[84:87], v[176:179], v[212:215], v[84:87]
	v_mfma_f32_16x16x32_bf16 v[80:83], v[184:187], v[212:215], v[80:83]
	v_mfma_f32_16x16x32_bf16 v[68:71], v[176:179], v[220:223], v[68:71]
	v_mfma_f32_16x16x32_bf16 v[64:67], v[184:187], v[220:223], v[64:67]
	v_mfma_f32_16x16x32_bf16 v[116:119], v[180:183], v[196:199], v[116:119]
	v_mfma_f32_16x16x32_bf16 v[112:115], v[188:191], v[196:199], v[112:115]
	v_mfma_f32_16x16x32_bf16 v[100:103], v[180:183], v[208:211], v[100:103]
	v_mfma_f32_16x16x32_bf16 v[96:99], v[188:191], v[208:211], v[96:99]
	v_mfma_f32_16x16x32_bf16 v[84:87], v[180:183], v[216:219], v[84:87]
	v_mfma_f32_16x16x32_bf16 v[80:83], v[188:191], v[216:219], v[80:83]
	v_mfma_f32_16x16x32_bf16 v[68:71], v[180:183], v[224:227], v[68:71]
	v_mfma_f32_16x16x32_bf16 v[64:67], v[188:191], v[224:227], v[64:67]
	s_barrier
	s_add_i32 s34, s97, s17
	v_lshl_add_u64 v[164:165], s[88:89], 0, v[134:135]
	s_mov_b32 m0, s34
	ds_read_b128 v[192:195], v167 offset:16384
	ds_read_b128 v[196:199], v167 offset:17408
	ds_read_b128 v[204:207], v167 offset:18432
	ds_read_b128 v[208:211], v167 offset:19456
	ds_read_b128 v[212:215], v167 offset:20480
	ds_read_b128 v[216:219], v167 offset:21504
	ds_read_b128 v[220:223], v167 offset:22528
	ds_read_b128 v[224:227], v167 offset:23552
	global_load_lds_dwordx4 v[164:165], off
	s_add_i32 m0, s34, 0x2000
	s_add_u32 s34, s88, 0x80000
	v_lshl_add_u64 v[228:229], s[88:89], 0, v[146:147]
	s_addc_u32 s35, s89, 0
	s_add_i32 s52, s8, s17
	global_load_lds_dwordx4 v[228:229], off
	v_lshl_add_u64 v[230:231], s[34:35], 0, v[134:135]
	s_mov_b32 m0, s52
	v_lshl_add_u64 v[232:233], s[90:91], 0, v[144:145]
	global_load_lds_dwordx4 v[230:231], off
	v_lshl_add_u64 v[230:231], s[34:35], 0, v[146:147]
	s_add_i32 m0, s52, 0x2000
	s_nop 0
	global_load_lds_dwordx4 v[230:231], off
	v_lshl_add_u64 v[230:231], s[90:91], 0, v[130:131]
	s_mov_b32 m0, s28
	s_nop 0
	global_load_lds_dwordx4 v[230:231], off
	s_mov_b32 m0, s29
	s_nop 0
	global_load_lds_dwordx4 v[232:233], off
	s_waitcnt vmcnt(8)
	s_waitcnt lgkmcnt(0)
	s_barrier
; #define PG8_STAGE(bufoff, gbase, voff) do { _Pragma("unroll") for (int _i = 0; _i < 2; ++_i) \
;         __builtin_amdgcn_global_load_lds((const unsigned*)((const char*)(gbase) + (voff)[_i]), (LAS unsigned*)(lds + (bufoff) + ldsw + _i * 8192), 16, 0, 0); } while (0)
; #define PG8_LDA(dst, b, h) do { _Pragma("unroll") for (int m = 0; m < 4; ++m) _Pragma("unroll") for (int k = 0; k < 2; ++k) dst[m][k] = *(const LAS bf16x8*)(lds + PG8_SA(b, h) + aoff + m * 2048 + k * 1024); } while (0)
; #define PG8_LDB(dst, b, h) do { _Pragma("unroll") for (int n = 0; n < 2; ++n) _Pragma("unroll") for (int k = 0; k < 2; ++k) dst[n][k] = *(const LAS bf16x8*)(lds + PG8_SB(b, h) + boff + n * 2048 + k * 1024); } while (0)
; #define PG8_MMA(ai, bj, At, Bt) do { __builtin_amdgcn_s_setprio(1); _Pragma("unroll") for (int m = 0; m < 4; ++m) _Pragma("unroll") for (int n = 0; n < 2; ++n) _Pragma("unroll") for (int k = 0; k < 2; ++k) \
;         acc[ai][bj][m][n] = __builtin_amdgcn_mfma_f32_16x16x32_bf16(Bt[n][k], At[m][k], acc[ai][bj][m][n], 0, 0, 0); __builtin_amdgcn_s_setprio(0); } while (0)
; #define PG8_WAIT_V(n) asm volatile("s_waitcnt vmcnt(" #n ")" ::: "memory")
; #define PG8_WAIT_L(n) asm volatile("s_waitcnt lgkmcnt(" #n ")" ::: "memory")
; #define PG8_BAR __builtin_amdgcn_s_barrier()
; #define PG8_SCHED __builtin_amdgcn_sched_barrier(0)
; template <class Epi, bool ALIGN_EPI, class Hook = NoHook>
; __device__ __forceinline__ void gemm_phase(LAS unsigned char* lds, const Gemm g, const StaticOrder& S, const Epi& E, const Hook& HK = Hook()) {
;     ...
;             PG8_WAIT_V(8); PG8_WAIT_L(0); PG8_BAR; PG8_MMA(1, 0, At, B0); PG8_MMA(1, 1, At, B1); PG8_BAR; PG8_SCHED;
;             PG8_LDB(B0, 1, 0); PG8_LDB(B1, 1, 1); PG8_SCHED; PG8_LDA(At, 1, 0); PG8_STAGE(PG8_SA(0, 1), a2 + hstepA, voffA);
;             PG8_WAIT_V(8); PG8_WAIT_L(0); PG8_BAR; PG8_MMA(0, 0, At, B0); PG8_MMA(0, 1, At, B1); PG8_BAR; PG8_SCHED;
	s_waitcnt lgkmcnt(0)
	v_mfma_f32_16x16x32_bf16 v[60:63], v[156:159], v[192:195], v[60:63]
	v_mfma_f32_16x16x32_bf16 v[56:59], v[168:171], v[192:195], v[56:59]
	v_mfma_f32_16x16x32_bf16 v[44:47], v[156:159], v[204:207], v[44:47]
	v_mfma_f32_16x16x32_bf16 v[40:43], v[168:171], v[204:207], v[40:43]
	v_mfma_f32_16x16x32_bf16 v[28:31], v[156:159], v[212:215], v[28:31]
	v_mfma_f32_16x16x32_bf16 v[24:27], v[168:171], v[212:215], v[24:27]
	v_mfma_f32_16x16x32_bf16 v[12:15], v[156:159], v[220:223], v[12:15]
	v_mfma_f32_16x16x32_bf16 v[8:11], v[168:171], v[220:223], v[8:11]
	v_mfma_f32_16x16x32_bf16 v[60:63], v[160:163], v[196:199], v[60:63]
	v_mfma_f32_16x16x32_bf16 v[56:59], v[172:175], v[196:199], v[56:59]
	v_mfma_f32_16x16x32_bf16 v[44:47], v[160:163], v[208:211], v[44:47]
	v_mfma_f32_16x16x32_bf16 v[40:43], v[172:175], v[208:211], v[40:43]
	v_mfma_f32_16x16x32_bf16 v[28:31], v[160:163], v[216:219], v[28:31]
	v_mfma_f32_16x16x32_bf16 v[24:27], v[172:175], v[216:219], v[24:27]
	v_mfma_f32_16x16x32_bf16 v[12:15], v[160:163], v[224:227], v[12:15]
	v_mfma_f32_16x16x32_bf16 v[8:11], v[172:175], v[224:227], v[8:11]
	v_mfma_f32_16x16x32_bf16 v[52:55], v[176:179], v[192:195], v[52:55]
	v_mfma_f32_16x16x32_bf16 v[48:51], v[184:187], v[192:195], v[48:51]
	v_mfma_f32_16x16x32_bf16 v[36:39], v[176:179], v[204:207], v[36:39]
	v_mfma_f32_16x16x32_bf16 v[32:35], v[184:187], v[204:207], v[32:35]
	v_mfma_f32_16x16x32_bf16 v[20:23], v[176:179], v[212:215], v[20:23]
	v_mfma_f32_16x16x32_bf16 v[16:19], v[184:187], v[212:215], v[16:19]
	v_mfma_f32_16x16x32_bf16 v[4:7], v[176:179], v[220:223], v[4:7]
	v_mfma_f32_16x16x32_bf16 v[0:3], v[184:187], v[220:223], v[0:3]
	v_mfma_f32_16x16x32_bf16 v[52:55], v[180:183], v[196:199], v[52:55]
	v_mfma_f32_16x16x32_bf16 v[48:51], v[188:191], v[196:199], v[48:51]
	v_mfma_f32_16x16x32_bf16 v[36:39], v[180:183], v[208:211], v[36:39]
	v_mfma_f32_16x16x32_bf16 v[32:35], v[188:191], v[208:211], v[32:35]
	v_mfma_f32_16x16x32_bf16 v[20:23], v[180:183], v[216:219], v[20:23]
	v_mfma_f32_16x16x32_bf16 v[16:19], v[188:191], v[216:219], v[16:19]
	v_mfma_f32_16x16x32_bf16 v[4:7], v[180:183], v[224:227], v[4:7]
	v_mfma_f32_16x16x32_bf16 v[0:3], v[188:191], v[224:227], v[0:3]
	s_barrier
	s_add_i32 s52, 0, 0x18000
	s_add_i32 s53, 0, 0x1c000
	v_add_u32_e32 v172, s52, v133
	v_add_u32_e32 v188, s53, v133
	ds_read_b128 v[156:159], v172
	ds_read_b128 v[160:163], v172 offset:1024
	ds_read_b128 v[168:171], v172 offset:2048
	ds_read_b128 v[172:175], v172 offset:3072
	ds_read_b128 v[176:179], v188
	ds_read_b128 v[180:183], v188 offset:1024
	ds_read_b128 v[184:187], v188 offset:2048
	ds_read_b128 v[188:191], v188 offset:3072
	s_add_u32 s34, s90, 0x80000
	s_addc_u32 s35, s91, 0
	s_mov_b32 m0, s71
	v_lshl_add_u64 v[234:235], s[34:35], 0, v[130:131]
	ds_read_b128 v[192:195], v167 offset:32768
	ds_read_b128 v[196:199], v167 offset:33792
	ds_read_b128 v[204:207], v167 offset:34816
	ds_read_b128 v[208:211], v167 offset:35840
	ds_read_b128 v[212:215], v167 offset:36864
	ds_read_b128 v[216:219], v167 offset:37888
	ds_read_b128 v[220:223], v167 offset:38912
	ds_read_b128 v[224:227], v167 offset:39936
	global_load_lds_dwordx4 v[234:235], off
	v_lshl_add_u64 v[234:235], s[34:35], 0, v[144:145]
	s_mov_b32 m0, s82
	s_nop 0
	global_load_lds_dwordx4 v[234:235], off
	s_waitcnt vmcnt(8)
	s_waitcnt lgkmcnt(0)
	s_barrier
	s_waitcnt lgkmcnt(0)
	v_mfma_f32_16x16x32_bf16 v[124:127], v[156:159], v[192:195], v[124:127]
	v_mfma_f32_16x16x32_bf16 v[120:123], v[168:171], v[192:195], v[120:123]
	v_mfma_f32_16x16x32_bf16 v[108:111], v[156:159], v[204:207], v[108:111]
	v_mfma_f32_16x16x32_bf16 v[104:107], v[168:171], v[204:207], v[104:107]
	v_mfma_f32_16x16x32_bf16 v[92:95], v[156:159], v[212:215], v[92:95]
	v_mfma_f32_16x16x32_bf16 v[88:91], v[168:171], v[212:215], v[88:91]
	v_mfma_f32_16x16x32_bf16 v[76:79], v[156:159], v[220:223], v[76:79]
	v_mfma_f32_16x16x32_bf16 v[72:75], v[168:171], v[220:223], v[72:75]
	v_mfma_f32_16x16x32_bf16 v[124:127], v[160:163], v[196:199], v[124:127]
	v_mfma_f32_16x16x32_bf16 v[120:123], v[172:175], v[196:199], v[120:123]
	v_mfma_f32_16x16x32_bf16 v[108:111], v[160:163], v[208:211], v[108:111]
	v_mfma_f32_16x16x32_bf16 v[104:107], v[172:175], v[208:211], v[104:107]
	v_mfma_f32_16x16x32_bf16 v[92:95], v[160:163], v[216:219], v[92:95]
	v_mfma_f32_16x16x32_bf16 v[88:91], v[172:175], v[216:219], v[88:91]
	v_mfma_f32_16x16x32_bf16 v[76:79], v[160:163], v[224:227], v[76:79]
	v_mfma_f32_16x16x32_bf16 v[72:75], v[172:175], v[224:227], v[72:75]
	v_mfma_f32_16x16x32_bf16 v[116:119], v[176:179], v[192:195], v[116:119]
	v_mfma_f32_16x16x32_bf16 v[112:115], v[184:187], v[192:195], v[112:115]
	v_mfma_f32_16x16x32_bf16 v[100:103], v[176:179], v[204:207], v[100:103]
	v_mfma_f32_16x16x32_bf16 v[96:99], v[184:187], v[204:207], v[96:99]
	v_mfma_f32_16x16x32_bf16 v[84:87], v[176:179], v[212:215], v[84:87]
	v_mfma_f32_16x16x32_bf16 v[80:83], v[184:187], v[212:215], v[80:83]
	v_mfma_f32_16x16x32_bf16 v[68:71], v[176:179], v[220:223], v[68:71]
	v_mfma_f32_16x16x32_bf16 v[64:67], v[184:187], v[220:223], v[64:67]
	v_mfma_f32_16x16x32_bf16 v[116:119], v[180:183], v[196:199], v[116:119]
	v_mfma_f32_16x16x32_bf16 v[112:115], v[188:191], v[196:199], v[112:115]
	v_mfma_f32_16x16x32_bf16 v[100:103], v[180:183], v[208:211], v[100:103]
	v_mfma_f32_16x16x32_bf16 v[96:99], v[188:191], v[208:211], v[96:99]
	v_mfma_f32_16x16x32_bf16 v[84:87], v[180:183], v[216:219], v[84:87]
	v_mfma_f32_16x16x32_bf16 v[80:83], v[188:191], v[216:219], v[80:83]
	v_mfma_f32_16x16x32_bf16 v[68:71], v[180:183], v[224:227], v[68:71]
	v_mfma_f32_16x16x32_bf16 v[64:67], v[188:191], v[224:227], v[64:67]
	s_barrier
; #define PG8_STAGE(bufoff, gbase, voff) do { _Pragma("unroll") for (int _i = 0; _i < 2; ++_i) \
;         __builtin_amdgcn_global_load_lds((const unsigned*)((const char*)(gbase) + (voff)[_i]), (LAS unsigned*)(lds + (bufoff) + ldsw + _i * 8192), 16, 0, 0); } while (0)
; #define PG8_LDA(dst, b, h) do { _Pragma("unroll") for (int m = 0; m < 4; ++m) _Pragma("unroll") for (int k = 0; k < 2; ++k) dst[m][k] = *(const LAS bf16x8*)(lds + PG8_SA(b, h) + aoff + m * 2048 + k * 1024); } while (0)
; #define PG8_MMA(ai, bj, At, Bt) do { __builtin_amdgcn_s_setprio(1); _Pragma("unroll") for (int m = 0; m < 4; ++m) _Pragma("unroll") for (int n = 0; n < 2; ++n) _Pragma("unroll") for (int k = 0; k < 2; ++k) \
;         acc[ai][bj][m][n] = __builtin_amdgcn_mfma_f32_16x16x32_bf16(Bt[n][k], At[m][k], acc[ai][bj][m][n], 0, 0, 0); __builtin_amdgcn_s_setprio(0); } while (0)
; #define PG8_WAIT_V(n) asm volatile("s_waitcnt vmcnt(" #n ")" ::: "memory")
; #define PG8_WAIT_L(n) asm volatile("s_waitcnt lgkmcnt(" #n ")" ::: "memory")
; #define PG8_BAR __builtin_amdgcn_s_barrier()
; #define PG8_SCHED __builtin_amdgcn_sched_barrier(0)
;     __device__ __forceinline__ void operator()(const f32x4 (&acc)[2][2][4][2], const Unit& u, int wr, int wc, int fr, int fq) const {
;         bf16_t* base = qkva; int ldc = 3072, colt; bool sg = false;
;         if (u.pn < 12) { colt = u.pn * BM; } else if (u.pn < 24) { base = bb; colt = (u.pn - 12) * BM; } else { colt = (u.pn - 24) * BM; sg = true; }
; template <class Epi, bool ALIGN_EPI, class Hook = NoHook>
; __device__ __forceinline__ void gemm_phase(LAS unsigned char* lds, const Gemm g, const StaticOrder& S, const Epi& E, const Hook& HK = Hook()) {
;     ...
;             PG8_LDA(At, 1, 1); PG8_STAGE(PG8_SB(1, 0), b3, voffB); PG8_STAGE(PG8_SB(1, 1), b3 + hstepB, voffB); PG8_STAGE(PG8_SA(1, 0), a3, voffA);
;             PG8_WAIT_V(8); PG8_WAIT_L(0); PG8_BAR; PG8_MMA(1, 0, At, B0); PG8_MMA(1, 1, At, B1); PG8_BAR; PG8_SCHED;
;         }
;         if constexpr (ALIGN_EPI) { if (wr == 0) PG8_BAR; }
;         E(acc, cur, wr, wc, fr, fq);
	s_add_i32 s34, s52, s17
	v_lshl_add_u64 v[164:165], v[164:165], 0, s[12:13]
	s_mov_b32 m0, s34
	ds_read_b128 v[192:195], v167 offset:49152
	ds_read_b128 v[196:199], v167 offset:50176
	ds_read_b128 v[204:207], v167 offset:51200
	ds_read_b128 v[208:211], v167 offset:52224
	ds_read_b128 v[212:215], v167 offset:53248
	ds_read_b128 v[216:219], v167 offset:54272
	ds_read_b128 v[220:223], v167 offset:55296
	ds_read_b128 v[224:227], v167 offset:56320
	global_load_lds_dwordx4 v[164:165], off
	s_add_i32 m0, s34, 0x2000
	s_add_u32 s34, s88, 0x80080
	v_lshl_add_u64 v[164:165], v[228:229], 0, s[12:13]
	s_addc_u32 s35, s89, 0
	s_add_i32 s52, s53, s17
	global_load_lds_dwordx4 v[164:165], off
	v_lshl_add_u64 v[164:165], s[34:35], 0, v[134:135]
	s_mov_b32 m0, s52
	s_nop 0
	global_load_lds_dwordx4 v[164:165], off
	v_lshl_add_u64 v[164:165], s[34:35], 0, v[146:147]
	s_add_i32 m0, s52, 0x2000
	s_nop 0
	global_load_lds_dwordx4 v[164:165], off
	v_lshl_add_u64 v[164:165], v[230:231], 0, s[12:13]
	s_mov_b32 m0, s92
	s_nop 0
	global_load_lds_dwordx4 v[164:165], off
	v_lshl_add_u64 v[164:165], v[232:233], 0, s[12:13]
	s_mov_b32 m0, s93
	s_nop 0
	global_load_lds_dwordx4 v[164:165], off
	s_waitcnt vmcnt(8)
	s_waitcnt lgkmcnt(0)
	s_barrier
	s_waitcnt lgkmcnt(0)
	v_mfma_f32_16x16x32_bf16 v[60:63], v[156:159], v[192:195], v[60:63]
	v_mfma_f32_16x16x32_bf16 v[56:59], v[168:171], v[192:195], v[56:59]
	v_mfma_f32_16x16x32_bf16 v[44:47], v[156:159], v[204:207], v[44:47]
	v_mfma_f32_16x16x32_bf16 v[40:43], v[168:171], v[204:207], v[40:43]
	v_mfma_f32_16x16x32_bf16 v[28:31], v[156:159], v[212:215], v[28:31]
	v_mfma_f32_16x16x32_bf16 v[24:27], v[168:171], v[212:215], v[24:27]
	v_mfma_f32_16x16x32_bf16 v[12:15], v[156:159], v[220:223], v[12:15]
	v_mfma_f32_16x16x32_bf16 v[8:11], v[168:171], v[220:223], v[8:11]
	v_mfma_f32_16x16x32_bf16 v[60:63], v[160:163], v[196:199], v[60:63]
	v_mfma_f32_16x16x32_bf16 v[56:59], v[172:175], v[196:199], v[56:59]
	v_mfma_f32_16x16x32_bf16 v[44:47], v[160:163], v[208:211], v[44:47]
	v_mfma_f32_16x16x32_bf16 v[40:43], v[172:175], v[208:211], v[40:43]
	v_mfma_f32_16x16x32_bf16 v[28:31], v[160:163], v[216:219], v[28:31]
	v_mfma_f32_16x16x32_bf16 v[24:27], v[172:175], v[216:219], v[24:27]
	v_mfma_f32_16x16x32_bf16 v[12:15], v[160:163], v[224:227], v[12:15]
	v_mfma_f32_16x16x32_bf16 v[8:11], v[172:175], v[224:227], v[8:11]
	v_mfma_f32_16x16x32_bf16 v[52:55], v[176:179], v[192:195], v[52:55]
	v_mfma_f32_16x16x32_bf16 v[48:51], v[184:187], v[192:195], v[48:51]
	v_mfma_f32_16x16x32_bf16 v[36:39], v[176:179], v[204:207], v[36:39]
	v_mfma_f32_16x16x32_bf16 v[32:35], v[184:187], v[204:207], v[32:35]
	v_mfma_f32_16x16x32_bf16 v[20:23], v[176:179], v[212:215], v[20:23]
	v_mfma_f32_16x16x32_bf16 v[16:19], v[184:187], v[212:215], v[16:19]
	v_mfma_f32_16x16x32_bf16 v[4:7], v[176:179], v[220:223], v[4:7]
	v_mfma_f32_16x16x32_bf16 v[0:3], v[184:187], v[220:223], v[0:3]
	v_mfma_f32_16x16x32_bf16 v[52:55], v[180:183], v[196:199], v[52:55]
	v_mfma_f32_16x16x32_bf16 v[48:51], v[188:191], v[196:199], v[48:51]
	v_mfma_f32_16x16x32_bf16 v[36:39], v[180:183], v[208:211], v[36:39]
	v_mfma_f32_16x16x32_bf16 v[32:35], v[188:191], v[208:211], v[32:35]
	v_mfma_f32_16x16x32_bf16 v[20:23], v[180:183], v[216:219], v[20:23]
	v_mfma_f32_16x16x32_bf16 v[16:19], v[188:191], v[216:219], v[16:19]
	v_mfma_f32_16x16x32_bf16 v[4:7], v[180:183], v[224:227], v[4:7]
	v_mfma_f32_16x16x32_bf16 v[0:3], v[188:191], v[224:227], v[0:3]
	s_barrier
	s_add_i32 s51, s51, 2
	s_add_u32 s86, s86, 0x100
	s_addc_u32 s87, s87, 0
	s_add_u32 s27, s27, 0x100
	s_addc_u32 s50, s50, 0
	s_cmp_gt_u32 s51, 29
	s_cbranch_scc0 .LBB0_270
	s_and_b64 vcc, exec, s[14:15]
	s_cbranch_vccz .LBB0_273
.LBB0_273:
	s_cmp_gt_i32 s84, 11
	s_mov_b64 s[50:51], -1
	s_cbranch_scc0 .LBB0_279
	s_lshl_b32 s19, s84, 8
	s_cmp_gt_u32 s84, 23
	s_mov_b64 s[72:73], -1
	s_mov_b64 s[26:27], -1
	s_cbranch_scc0 .LBB0_276
	s_add_i32 s5, s19, 0xffffe800
	s_mov_b64 s[26:27], 0

; #define PG8_BAR __builtin_amdgcn_s_barrier()
; template <class Epi, bool ALIGN_EPI, class Hook = NoHook>
; __device__ __forceinline__ void gemm_phase(LAS unsigned char* lds, const Gemm g, const StaticOrder& S, const Epi& E, const Hook& HK = Hook()) {
;     ...
;         if (!has_next) break;
; #pragma unroll
;         for (int a = 0; a < 2; ++a)
; #pragma unroll
;             for (int b = 0; b < 2; ++b)
; #pragma unroll
;                 for (int m = 0; m < 4; ++m)
; #pragma unroll
;                     for (int n = 0; n < 2; ++n) acc[a][b][m][n] = (f32x4){0.f, 0.f, 0.f, 0.f};
;         cur = nxt; cA = nA; cB = nB; ++ui;
;         if constexpr (ALIGN_EPI) { if (wr == 1) PG8_BAR; }
;     }
.LBB0_346:
	s_andn2_b64 vcc, exec, s[6:7]
	s_cbranch_vccnz .LBB0_265
	s_branch .LBB0_265

; __device__ __forceinline__ unsigned cvt_pk_bf16(float lo, float hi) { unsigned r; asm volatile("v_cvt_pk_bf16_f32 %0, %1, %2" : "=v"(r) : "v"(lo), "v"(hi)); return r; }
;     __device__ __forceinline__ void operator()(const f32x4 (&acc)[2][2][4][2], const Unit& u, int wr, int wc, int fr, int fq) const {
;         const int row0 = u.pm * BM + wr * 64 + fr; const int col0 = u.pn * BM + wc * 32 + 8 * fq;
; #pragma unroll
;         for (int ai = 0; ai < 2; ++ai) {
;             f32x4 p0[4][2], p1[4][2];
; #pragma unroll
;             for (int m = 0; m < 4; ++m)
; #pragma unroll
;                 for (int bj = 0; bj < 2; ++bj) {
;                     const size_t e = (size_t)(row0 + ai * HALF + m * 16) * 2048 + col0 + bj * HALF;
;                     if (IN_F32) { p0[m][bj] = *(const f32x4*)((const float*)base + e); p1[m][bj] = *(const f32x4*)((const float*)base + e + 4); }
;                     else { const u32x4 w = *(const u32x4*)((const bf16_t*)base + e); p0[m][bj] = (f32x4){bflo(w.x), bfhi(w.x), bflo(w.y), bfhi(w.y)}; p1[m][bj] = (f32x4){bflo(w.z), bfhi(w.z), bflo(w.w), bfhi(w.w)}; }
;                 }
; #pragma unroll
;             for (int m = 0; m < 4; ++m)
; #pragma unroll
;                 for (int bj = 0; bj < 2; ++bj) {
;                     const size_t e = (size_t)(row0 + ai * HALF + m * 16) * 2048 + col0 + bj * HALF;
;                     const f32x4 v0 = p0[m][bj] + acc[ai][bj][m][0] * scale, v1 = p1[m][bj] + acc[ai][bj][m][1] * scale;
;                     if (OUT_F32) { *(f32x4*)((float*)out + e) = v0; *(f32x4*)((float*)out + e + 4) = v1; }
;                     else { u32x4 w; w.x = cvt_pk_bf16(v0[0], v0[1]); w.y = cvt_pk_bf16(v0[2], v0[3]); w.z = cvt_pk_bf16(v1[0], v1[1]); w.w = cvt_pk_bf16(v1[2], v1[3]); *(u32x4*)((bf16_t*)out + e) = w; }
;                 }
.LBB0_790:
	v_lshl_or_b32 v152, s80, 8, v164
	v_lshl_add_u32 v158, s38, 8, v141
	v_ashrrev_i32_e32 v153, 31, v152
	v_lshlrev_b64 v[152:153], 1, v[152:153]
	v_ashrrev_i32_e32 v159, 31, v158
	v_lshl_add_u64 v[154:155], s[60:61], 0, v[152:153]
	v_lshlrev_b64 v[156:157], 12, v[158:159]
	v_lshl_add_u64 v[160:161], v[154:155], 0, v[156:157]
	global_load_dwordx4 v[168:171], v[160:161], off
	global_load_dwordx4 v[172:175], v[160:161], off offset:256
	v_or_b32_e32 v160, 16, v158
	v_ashrrev_i32_e32 v161, 31, v160
	v_lshlrev_b64 v[208:209], 12, v[160:161]
	v_lshl_add_u64 v[160:161], v[154:155], 0, v[208:209]
	global_load_dwordx4 v[176:179], v[160:161], off
	global_load_dwordx4 v[180:183], v[160:161], off offset:256
	v_or_b32_e32 v160, 32, v158
	v_ashrrev_i32_e32 v161, 31, v160
	v_lshlrev_b64 v[160:161], 12, v[160:161]
	v_lshl_add_u64 v[162:163], v[154:155], 0, v[160:161]
	global_load_dwordx4 v[184:187], v[162:163], off
	global_load_dwordx4 v[188:191], v[162:163], off offset:256
	v_or_b32_e32 v158, 48, v158
	v_ashrrev_i32_e32 v159, 31, v158
	v_lshlrev_b64 v[158:159], 12, v[158:159]
	v_lshl_add_u64 v[162:163], v[154:155], 0, v[158:159]
	global_load_dwordx4 v[192:195], v[162:163], off
	global_load_dwordx4 v[196:199], v[162:163], off offset:256
	s_andn2_b64 vcc, exec, s[0:1]
	s_mov_b64 s[0:1], -1
	s_waitcnt vmcnt(0)
	v_lshlrev_b32_e32 v210, 16, v168
	v_and_b32_e32 v211, 0xffff0000, v168
	v_lshlrev_b32_e32 v168, 16, v169
	v_and_b32_e32 v169, 0xffff0000, v169
	v_lshlrev_b32_e32 v212, 16, v170
	v_and_b32_e32 v213, 0xffff0000, v170
	v_lshlrev_b32_e32 v170, 16, v171
	v_and_b32_e32 v171, 0xffff0000, v171
	v_pk_add_f32 v[124:125], v[124:125], v[210:211]
	v_pk_add_f32 v[126:127], v[126:127], v[168:169]
	v_pk_add_f32 v[168:169], v[122:123], v[170:171]
	v_pk_add_f32 v[122:123], v[120:121], v[212:213]
	v_cvt_pk_bf16_f32 v120, v124, v125
	v_lshl_add_u64 v[124:125], s[76:77], 0, v[156:157]
	v_lshlrev_b32_e32 v214, 16, v172
	v_and_b32_e32 v215, 0xffff0000, v172
	v_lshlrev_b32_e32 v172, 16, v173
	v_and_b32_e32 v173, 0xffff0000, v173
	v_lshlrev_b32_e32 v216, 16, v174
	v_and_b32_e32 v217, 0xffff0000, v174
	v_lshlrev_b32_e32 v174, 16, v175
	v_and_b32_e32 v175, 0xffff0000, v175
	v_cvt_pk_bf16_f32 v121, v126, v127
	v_lshl_add_u64 v[124:125], v[124:125], 0, v[152:153]
	v_lshlrev_b32_e32 v218, 16, v176
	v_and_b32_e32 v219, 0xffff0000, v176
	v_lshlrev_b32_e32 v176, 16, v177
	v_and_b32_e32 v177, 0xffff0000, v177
	v_cvt_pk_bf16_f32 v122, v122, v123
	v_cvt_pk_bf16_f32 v123, v168, v169
	global_store_dwordx4 v[124:125], v[120:123], off
	v_pk_add_f32 v[118:119], v[118:119], v[172:173]
	v_pk_add_f32 v[116:117], v[116:117], v[214:215]
	v_pk_add_f32 v[120:121], v[110:111], v[174:175]
	v_pk_add_f32 v[110:111], v[108:109], v[216:217]
	v_cvt_pk_bf16_f32 v108, v116, v117
	v_cvt_pk_bf16_f32 v109, v118, v119
	v_lshlrev_b32_e32 v220, 16, v178
	v_and_b32_e32 v221, 0xffff0000, v178
	v_lshlrev_b32_e32 v178, 16, v179
	v_and_b32_e32 v179, 0xffff0000, v179
	v_cvt_pk_bf16_f32 v110, v110, v111
	v_cvt_pk_bf16_f32 v111, v120, v121
	global_store_dwordx4 v[124:125], v[108:111], off offset:256
	v_lshlrev_b32_e32 v222, 16, v180
	v_and_b32_e32 v223, 0xffff0000, v180
	v_pk_add_f32 v[108:109], v[114:115], v[176:177]
	v_pk_add_f32 v[110:111], v[112:113], v[218:219]
	v_pk_add_f32 v[112:113], v[106:107], v[178:179]
	v_pk_add_f32 v[106:107], v[104:105], v[220:221]
	v_cvt_pk_bf16_f32 v104, v110, v111
	v_cvt_pk_bf16_f32 v105, v108, v109
	v_lshl_add_u64 v[108:109], s[76:77], 0, v[208:209]
	v_lshlrev_b32_e32 v180, 16, v181
	v_and_b32_e32 v181, 0xffff0000, v181
	v_lshlrev_b32_e32 v224, 16, v182
	v_and_b32_e32 v225, 0xffff0000, v182
	v_lshlrev_b32_e32 v182, 16, v183
	v_and_b32_e32 v183, 0xffff0000, v183
	v_lshl_add_u64 v[108:109], v[108:109], 0, v[152:153]
	v_lshlrev_b32_e32 v226, 16, v184
	v_and_b32_e32 v227, 0xffff0000, v184
	v_lshlrev_b32_e32 v184, 16, v185
	v_and_b32_e32 v185, 0xffff0000, v185
	v_cvt_pk_bf16_f32 v106, v106, v107
	v_cvt_pk_bf16_f32 v107, v112, v113
	global_store_dwordx4 v[108:109], v[104:107], off
	v_pk_add_f32 v[102:103], v[102:103], v[180:181]
	v_pk_add_f32 v[100:101], v[100:101], v[222:223]
	v_pk_add_f32 v[104:105], v[94:95], v[182:183]
	v_pk_add_f32 v[94:95], v[92:93], v[224:225]
	v_cvt_pk_bf16_f32 v92, v100, v101
	v_cvt_pk_bf16_f32 v93, v102, v103
	v_lshlrev_b32_e32 v228, 16, v186
	v_and_b32_e32 v229, 0xffff0000, v186
	v_lshlrev_b32_e32 v186, 16, v187
	v_and_b32_e32 v187, 0xffff0000, v187
	v_cvt_pk_bf16_f32 v94, v94, v95
	v_cvt_pk_bf16_f32 v95, v104, v105
	global_store_dwordx4 v[108:109], v[92:95], off offset:256
	v_lshlrev_b32_e32 v230, 16, v188
	v_and_b32_e32 v231, 0xffff0000, v188
	v_pk_add_f32 v[92:93], v[98:99], v[184:185]
	v_pk_add_f32 v[94:95], v[96:97], v[226:227]
	v_pk_add_f32 v[96:97], v[90:91], v[186:187]
	v_pk_add_f32 v[90:91], v[88:89], v[228:229]
	v_cvt_pk_bf16_f32 v88, v94, v95
	v_cvt_pk_bf16_f32 v89, v92, v93
	v_lshl_add_u64 v[92:93], s[76:77], 0, v[160:161]
	v_lshlrev_b32_e32 v188, 16, v189
	v_and_b32_e32 v189, 0xffff0000, v189
	v_lshlrev_b32_e32 v232, 16, v190
	v_and_b32_e32 v233, 0xffff0000, v190
	v_lshlrev_b32_e32 v190, 16, v191
	v_and_b32_e32 v191, 0xffff0000, v191
	v_lshl_add_u64 v[92:93], v[92:93], 0, v[152:153]
	v_lshlrev_b32_e32 v234, 16, v192
	v_and_b32_e32 v235, 0xffff0000, v192
	v_lshlrev_b32_e32 v192, 16, v193
	v_and_b32_e32 v193, 0xffff0000, v193
	v_cvt_pk_bf16_f32 v90, v90, v91
	v_cvt_pk_bf16_f32 v91, v96, v97
	global_store_dwordx4 v[92:93], v[88:91], off
	v_pk_add_f32 v[86:87], v[86:87], v[188:189]
	v_pk_add_f32 v[84:85], v[84:85], v[230:231]
	v_pk_add_f32 v[88:89], v[78:79], v[190:191]
	v_pk_add_f32 v[78:79], v[76:77], v[232:233]
	v_cvt_pk_bf16_f32 v76, v84, v85
; __device__ __forceinline__ unsigned cvt_pk_bf16(float lo, float hi) { unsigned r; asm volatile("v_cvt_pk_bf16_f32 %0, %1, %2" : "=v"(r) : "v"(lo), "v"(hi)); return r; }
;     __device__ __forceinline__ void operator()(const f32x4 (&acc)[2][2][4][2], const Unit& u, int wr, int wc, int fr, int fq) const {
;     ...
;         for (int ai = 0; ai < 2; ++ai) {
;             f32x4 p0[4][2], p1[4][2];
; #pragma unroll
;             for (int m = 0; m < 4; ++m)
; #pragma unroll
;                 for (int bj = 0; bj < 2; ++bj) {
;                     const size_t e = (size_t)(row0 + ai * HALF + m * 16) * 2048 + col0 + bj * HALF;
;                     if (IN_F32) { p0[m][bj] = *(const f32x4*)((const float*)base + e); p1[m][bj] = *(const f32x4*)((const float*)base + e + 4); }
;                     else { const u32x4 w = *(const u32x4*)((const bf16_t*)base + e); p0[m][bj] = (f32x4){bflo(w.x), bfhi(w.x), bflo(w.y), bfhi(w.y)}; p1[m][bj] = (f32x4){bflo(w.z), bfhi(w.z), bflo(w.w), bfhi(w.w)}; }
;                 }
; #pragma unroll
;             for (int m = 0; m < 4; ++m)
; #pragma unroll
;                 for (int bj = 0; bj < 2; ++bj) {
;                     const size_t e = (size_t)(row0 + ai * HALF + m * 16) * 2048 + col0 + bj * HALF;
;                     const f32x4 v0 = p0[m][bj] + acc[ai][bj][m][0] * scale, v1 = p1[m][bj] + acc[ai][bj][m][1] * scale;
;                     if (OUT_F32) { *(f32x4*)((float*)out + e) = v0; *(f32x4*)((float*)out + e + 4) = v1; }
;                     else { u32x4 w; w.x = cvt_pk_bf16(v0[0], v0[1]); w.y = cvt_pk_bf16(v0[2], v0[3]); w.z = cvt_pk_bf16(v1[0], v1[1]); w.w = cvt_pk_bf16(v1[2], v1[3]); *(u32x4*)((bf16_t*)out + e) = w; }
;                 }
	v_cvt_pk_bf16_f32 v77, v86, v87
	v_lshlrev_b32_e32 v236, 16, v194
	v_and_b32_e32 v237, 0xffff0000, v194
	v_lshlrev_b32_e32 v194, 16, v195
	v_and_b32_e32 v195, 0xffff0000, v195
	v_cvt_pk_bf16_f32 v78, v78, v79
	v_cvt_pk_bf16_f32 v79, v88, v89
	global_store_dwordx4 v[92:93], v[76:79], off offset:256
	v_lshlrev_b32_e32 v238, 16, v196
	v_and_b32_e32 v239, 0xffff0000, v196
	v_pk_add_f32 v[76:77], v[82:83], v[192:193]
	v_pk_add_f32 v[78:79], v[80:81], v[234:235]
	v_pk_add_f32 v[80:81], v[74:75], v[194:195]
	v_pk_add_f32 v[74:75], v[72:73], v[236:237]
	v_cvt_pk_bf16_f32 v72, v78, v79
	v_cvt_pk_bf16_f32 v73, v76, v77
	v_lshl_add_u64 v[76:77], s[76:77], 0, v[158:159]
	v_lshlrev_b32_e32 v196, 16, v197
	v_and_b32_e32 v197, 0xffff0000, v197
	v_lshlrev_b32_e32 v162, 16, v198
	v_and_b32_e32 v163, 0xffff0000, v198
	v_lshlrev_b32_e32 v198, 16, v199
	v_and_b32_e32 v199, 0xffff0000, v199
	v_lshl_add_u64 v[76:77], v[76:77], 0, v[152:153]
	v_cvt_pk_bf16_f32 v74, v74, v75
	v_cvt_pk_bf16_f32 v75, v80, v81
	global_store_dwordx4 v[76:77], v[72:75], off
	v_pk_add_f32 v[70:71], v[70:71], v[196:197]
	v_pk_add_f32 v[68:69], v[68:69], v[238:239]
	v_pk_add_f32 v[72:73], v[66:67], v[198:199]
	v_pk_add_f32 v[66:67], v[64:65], v[162:163]
	v_cvt_pk_bf16_f32 v64, v68, v69
	v_cvt_pk_bf16_f32 v65, v70, v71
	v_lshl_add_u64 v[100:101], v[156:157], 0, s[6:7]
	v_cvt_pk_bf16_f32 v66, v66, v67
	v_cvt_pk_bf16_f32 v67, v72, v73
	global_store_dwordx4 v[76:77], v[64:67], off offset:256
	v_lshl_add_u64 v[102:103], v[156:157], 0, s[14:15]
	s_nop 0
	v_lshl_add_u64 v[64:65], v[154:155], 0, v[100:101]
	global_load_dwordx4 v[68:71], v[64:65], off
	global_load_dwordx4 v[72:75], v[64:65], off offset:256
	v_lshl_add_u64 v[64:65], v[154:155], 0, v[102:103]
	global_load_dwordx4 v[76:79], v[64:65], off
	global_load_dwordx4 v[80:83], v[64:65], off offset:256
	v_lshl_add_u64 v[66:67], v[156:157], 0, s[16:17]
	v_lshl_add_u64 v[64:65], v[154:155], 0, v[66:67]
	global_load_dwordx4 v[84:87], v[64:65], off
	global_load_dwordx4 v[88:91], v[64:65], off offset:256
	v_lshl_add_u64 v[64:65], v[156:157], 0, s[18:19]
	v_lshl_add_u64 v[96:97], v[154:155], 0, v[64:65]
	global_load_dwordx4 v[92:95], v[96:97], off
	s_nop 0
	global_load_dwordx4 v[96:99], v[96:97], off offset:256
	s_waitcnt vmcnt(7)
	v_lshlrev_b32_e32 v104, 16, v68
	v_and_b32_e32 v105, 0xffff0000, v68
	v_lshlrev_b32_e32 v108, 16, v70
	v_and_b32_e32 v109, 0xffff0000, v70
	v_lshlrev_b32_e32 v70, 16, v71
	v_and_b32_e32 v71, 0xffff0000, v71
	v_pk_add_f32 v[60:61], v[60:61], v[104:105]
	v_lshlrev_b32_e32 v106, 16, v69
	v_and_b32_e32 v107, 0xffff0000, v69
	v_pk_add_f32 v[70:71], v[58:59], v[70:71]
	v_pk_add_f32 v[58:59], v[56:57], v[108:109]
	v_cvt_pk_bf16_f32 v56, v60, v61
	v_lshl_add_u64 v[60:61], s[76:77], 0, v[100:101]
	s_waitcnt vmcnt(6)
	v_lshlrev_b32_e32 v110, 16, v72
	v_and_b32_e32 v111, 0xffff0000, v72
	v_lshlrev_b32_e32 v72, 16, v73
	v_and_b32_e32 v73, 0xffff0000, v73
	v_lshlrev_b32_e32 v112, 16, v74
	v_and_b32_e32 v113, 0xffff0000, v74
	v_lshlrev_b32_e32 v74, 16, v75
	v_and_b32_e32 v75, 0xffff0000, v75
	v_pk_add_f32 v[62:63], v[62:63], v[106:107]
	v_lshl_add_u64 v[60:61], v[60:61], 0, v[152:153]
	v_cvt_pk_bf16_f32 v57, v62, v63
	s_waitcnt vmcnt(5)
	v_lshlrev_b32_e32 v114, 16, v76
	v_and_b32_e32 v115, 0xffff0000, v76
	v_lshlrev_b32_e32 v76, 16, v77
	v_and_b32_e32 v77, 0xffff0000, v77
	v_cvt_pk_bf16_f32 v58, v58, v59
	v_cvt_pk_bf16_f32 v59, v70, v71
	global_store_dwordx4 v[60:61], v[56:59], off
	v_pk_add_f32 v[54:55], v[54:55], v[72:73]
	v_pk_add_f32 v[52:53], v[52:53], v[110:111]
	v_pk_add_f32 v[56:57], v[46:47], v[74:75]
	v_pk_add_f32 v[46:47], v[44:45], v[112:113]
	v_cvt_pk_bf16_f32 v44, v52, v53
	v_cvt_pk_bf16_f32 v45, v54, v55
	v_lshlrev_b32_e32 v116, 16, v78
	v_and_b32_e32 v117, 0xffff0000, v78
	v_lshlrev_b32_e32 v78, 16, v79
	v_and_b32_e32 v79, 0xffff0000, v79
	v_cvt_pk_bf16_f32 v46, v46, v47
	v_cvt_pk_bf16_f32 v47, v56, v57
	global_store_dwordx4 v[60:61], v[44:47], off offset:256
	s_waitcnt vmcnt(6)
; #define PG8_WAIT_V(n) asm volatile("s_waitcnt vmcnt(" #n ")" ::: "memory")
; #define PG8_BAR __builtin_amdgcn_s_barrier()
;     __device__ __forceinline__ void operator()(const f32x4 (&acc)[2][2][4][2], const Unit& u, int wr, int wc, int fr, int fq) const {
;     ...
;         for (int ai = 0; ai < 2; ++ai) {
;             f32x4 p0[4][2], p1[4][2];
; #pragma unroll
;             for (int m = 0; m < 4; ++m)
; #pragma unroll
;                 for (int bj = 0; bj < 2; ++bj) {
;                     const size_t e = (size_t)(row0 + ai * HALF + m * 16) * 2048 + col0 + bj * HALF;
;                     if (IN_F32) { p0[m][bj] = *(const f32x4*)((const float*)base + e); p1[m][bj] = *(const f32x4*)((const float*)base + e + 4); }
;                     else { const u32x4 w = *(const u32x4*)((const bf16_t*)base + e); p0[m][bj] = (f32x4){bflo(w.x), bfhi(w.x), bflo(w.y), bfhi(w.y)}; p1[m][bj] = (f32x4){bflo(w.z), bfhi(w.z), bflo(w.w), bfhi(w.w)}; }
;                 }
; #pragma unroll
;             for (int m = 0; m < 4; ++m)
; #pragma unroll
;                 for (int bj = 0; bj < 2; ++bj) {
;                     const size_t e = (size_t)(row0 + ai * HALF + m * 16) * 2048 + col0 + bj * HALF;
;                     const f32x4 v0 = p0[m][bj] + acc[ai][bj][m][0] * scale, v1 = p1[m][bj] + acc[ai][bj][m][1] * scale;
;                     if (OUT_F32) { *(f32x4*)((float*)out + e) = v0; *(f32x4*)((float*)out + e + 4) = v1; }
;                     else { u32x4 w; w.x = cvt_pk_bf16(v0[0], v0[1]); w.y = cvt_pk_bf16(v0[2], v0[3]); w.z = cvt_pk_bf16(v1[0], v1[1]); w.w = cvt_pk_bf16(v1[2], v1[3]); *(u32x4*)((bf16_t*)out + e) = w; }
;                 }
; template <class Epi, bool ALIGN_EPI, class Hook = NoHook>
; __device__ __forceinline__ void gemm_phase(LAS unsigned char* lds, const Gemm g, const StaticOrder& S, const Epi& E, const Hook& HK = Hook()) {
;     ...
;         if (!has_next) break;
; #pragma unroll
;         for (int a = 0; a < 2; ++a)
; #pragma unroll
;             for (int b = 0; b < 2; ++b)
; #pragma unroll
;                 for (int m = 0; m < 4; ++m)
; #pragma unroll
;                     for (int n = 0; n < 2; ++n) acc[a][b][m][n] = (f32x4){0.f, 0.f, 0.f, 0.f};
;         cur = nxt; cA = nA; cB = nB; ++ui;
;         if constexpr (ALIGN_EPI) { if (wr == 1) PG8_BAR; }
;     }
;     PG8_WAIT_V(0);
;     if constexpr (!ALIGN_EPI) { if (wr == 0) PG8_BAR; }
;     PG8_BAR;
	v_lshlrev_b32_e32 v118, 16, v80
	v_and_b32_e32 v119, 0xffff0000, v80
	v_pk_add_f32 v[44:45], v[50:51], v[76:77]
	v_pk_add_f32 v[46:47], v[48:49], v[114:115]
	v_pk_add_f32 v[48:49], v[42:43], v[78:79]
	v_pk_add_f32 v[42:43], v[40:41], v[116:117]
	v_cvt_pk_bf16_f32 v40, v46, v47
	v_cvt_pk_bf16_f32 v41, v44, v45
	v_lshl_add_u64 v[44:45], s[76:77], 0, v[102:103]
	v_lshlrev_b32_e32 v80, 16, v81
	v_and_b32_e32 v81, 0xffff0000, v81
	v_lshlrev_b32_e32 v120, 16, v82
	v_and_b32_e32 v121, 0xffff0000, v82
	v_lshlrev_b32_e32 v82, 16, v83
	v_and_b32_e32 v83, 0xffff0000, v83
	v_lshl_add_u64 v[44:45], v[44:45], 0, v[152:153]
	s_waitcnt vmcnt(5)
	v_lshlrev_b32_e32 v122, 16, v84
	v_and_b32_e32 v123, 0xffff0000, v84
	v_lshlrev_b32_e32 v84, 16, v85
	v_and_b32_e32 v85, 0xffff0000, v85
	v_cvt_pk_bf16_f32 v42, v42, v43
	v_cvt_pk_bf16_f32 v43, v48, v49
	global_store_dwordx4 v[44:45], v[40:43], off
	v_pk_add_f32 v[38:39], v[38:39], v[80:81]
	v_pk_add_f32 v[36:37], v[36:37], v[118:119]
	v_pk_add_f32 v[40:41], v[30:31], v[82:83]
	v_pk_add_f32 v[30:31], v[28:29], v[120:121]
	v_cvt_pk_bf16_f32 v28, v36, v37
	v_cvt_pk_bf16_f32 v29, v38, v39
	v_lshlrev_b32_e32 v124, 16, v86
	v_and_b32_e32 v125, 0xffff0000, v86
	v_lshlrev_b32_e32 v86, 16, v87
	v_and_b32_e32 v87, 0xffff0000, v87
	v_cvt_pk_bf16_f32 v30, v30, v31
	v_cvt_pk_bf16_f32 v31, v40, v41
	global_store_dwordx4 v[44:45], v[28:31], off offset:256
	s_waitcnt vmcnt(6)
	v_lshlrev_b32_e32 v126, 16, v88
	v_and_b32_e32 v127, 0xffff0000, v88
	v_pk_add_f32 v[28:29], v[34:35], v[84:85]
	v_pk_add_f32 v[30:31], v[32:33], v[122:123]
	v_pk_add_f32 v[32:33], v[26:27], v[86:87]
	v_pk_add_f32 v[26:27], v[24:25], v[124:125]
	v_cvt_pk_bf16_f32 v24, v30, v31
	v_cvt_pk_bf16_f32 v25, v28, v29
	v_lshl_add_u64 v[28:29], s[76:77], 0, v[66:67]
	v_lshlrev_b32_e32 v88, 16, v89
	v_and_b32_e32 v89, 0xffff0000, v89
	v_lshlrev_b32_e32 v154, 16, v90
	v_and_b32_e32 v155, 0xffff0000, v90
	v_lshlrev_b32_e32 v90, 16, v91
	v_and_b32_e32 v91, 0xffff0000, v91
	v_lshl_add_u64 v[28:29], v[28:29], 0, v[152:153]
	s_waitcnt vmcnt(5)
	v_lshlrev_b32_e32 v156, 16, v92
	v_and_b32_e32 v157, 0xffff0000, v92
	v_lshlrev_b32_e32 v92, 16, v93
	v_and_b32_e32 v93, 0xffff0000, v93
	v_cvt_pk_bf16_f32 v26, v26, v27
	v_cvt_pk_bf16_f32 v27, v32, v33
	global_store_dwordx4 v[28:29], v[24:27], off
	v_pk_add_f32 v[22:23], v[22:23], v[88:89]
	v_pk_add_f32 v[20:21], v[20:21], v[126:127]
	v_pk_add_f32 v[24:25], v[14:15], v[90:91]
	v_pk_add_f32 v[14:15], v[12:13], v[154:155]
	v_cvt_pk_bf16_f32 v12, v20, v21
	v_cvt_pk_bf16_f32 v13, v22, v23
	v_lshlrev_b32_e32 v158, 16, v94
	v_and_b32_e32 v159, 0xffff0000, v94
	v_lshlrev_b32_e32 v94, 16, v95
	v_and_b32_e32 v95, 0xffff0000, v95
	v_cvt_pk_bf16_f32 v14, v14, v15
	v_cvt_pk_bf16_f32 v15, v24, v25
	global_store_dwordx4 v[28:29], v[12:15], off offset:256
	s_waitcnt vmcnt(6)
	v_lshlrev_b32_e32 v68, 16, v98
	v_and_b32_e32 v69, 0xffff0000, v98
	v_pk_add_f32 v[12:13], v[18:19], v[92:93]
	v_pk_add_f32 v[14:15], v[16:17], v[156:157]
	v_pk_add_f32 v[16:17], v[10:11], v[94:95]
	v_pk_add_f32 v[10:11], v[8:9], v[158:159]
	v_cvt_pk_bf16_f32 v8, v14, v15
	v_cvt_pk_bf16_f32 v9, v12, v13
	v_lshl_add_u64 v[12:13], s[76:77], 0, v[64:65]
	v_lshlrev_b32_e32 v98, 16, v99
	v_and_b32_e32 v99, 0xffff0000, v99
	v_lshl_add_u64 v[12:13], v[12:13], 0, v[152:153]
	v_lshlrev_b32_e32 v160, 16, v96
	v_and_b32_e32 v161, 0xffff0000, v96
	v_lshlrev_b32_e32 v96, 16, v97
	v_and_b32_e32 v97, 0xffff0000, v97
	v_cvt_pk_bf16_f32 v10, v10, v11
	v_cvt_pk_bf16_f32 v11, v16, v17
	global_store_dwordx4 v[12:13], v[8:11], off
	v_pk_add_f32 v[6:7], v[6:7], v[96:97]
	v_pk_add_f32 v[4:5], v[4:5], v[160:161]
	v_pk_add_f32 v[8:9], v[2:3], v[98:99]
	v_pk_add_f32 v[2:3], v[0:1], v[68:69]
	v_cvt_pk_bf16_f32 v0, v4, v5
	v_cvt_pk_bf16_f32 v1, v6, v7
	s_nop 0
	v_cvt_pk_bf16_f32 v2, v2, v3
	v_cvt_pk_bf16_f32 v3, v8, v9
	global_store_dwordx4 v[12:13], v[0:3], off offset:256
	s_cbranch_vccnz .LBB0_779
	s_andn2_b64 vcc, exec, s[8:9]
	s_cbranch_vccnz .LBB0_778
	s_branch .LBB0_778
.LBB0_793:
	s_cmp_lg_u64 s[12:13], 0
	s_cbranch_scc0 .Lnoalign_skip_P8
	s_barrier

; __device__ __forceinline__ unsigned cvt_pk_bf16(float lo, float hi) { unsigned r; asm volatile("v_cvt_pk_bf16_f32 %0, %1, %2" : "=v"(r) : "v"(lo), "v"(hi)); return r; }
;     __device__ __forceinline__ void operator()(const f32x4 (&acc)[2][2][4][2], const Unit& u, int wr, int wc, int fr, int fq) const {
;         const int row0 = u.pm * BM + wr * 64 + fr; const int col0 = u.pn * HALF + wc * 32 + 8 * fq;
; #pragma unroll
;         for (int ai = 0; ai < 2; ++ai)
; #pragma unroll
;             for (int m = 0; m < 4; ++m) {
;                 bf16_t* rowp = O + (size_t)(row0 + ai * HALF + m * 16) * ldc + col0;
;                 const f32x4 g0 = acc[ai][0][m][0], g1 = acc[ai][0][m][1], u0 = acc[ai][1][m][0], u1 = acc[ai][1][m][1];
;                 const f32x2 a = silu_mul_pk((f32x2){g0[0], g0[1]}, (f32x2){u0[0], u0[1]}), b = silu_mul_pk((f32x2){g0[2], g0[3]}, (f32x2){u0[2], u0[3]});
;                 const f32x2 c = silu_mul_pk((f32x2){g1[0], g1[1]}, (f32x2){u1[0], u1[1]}), d = silu_mul_pk((f32x2){g1[2], g1[3]}, (f32x2){u1[2], u1[3]});
;                 u32x4 w; w.x = cvt_pk_bf16(a.x, a.y); w.y = cvt_pk_bf16(b.x, b.y); w.z = cvt_pk_bf16(c.x, c.y); w.w = cvt_pk_bf16(d.x, d.y);
;                 *(u32x4*)rowp = w;
;             }
.LBB0_922:
	v_pk_mul_f32 v[158:159], v[124:125], s[12:13] op_sel_hi:[1,0]
	v_pk_mul_f32 v[160:161], v[126:127], s[12:13] op_sel_hi:[1,0]
	v_exp_f32_e32 v158, v158
	v_exp_f32_e32 v159, v159
	v_exp_f32_e32 v160, v160
	v_exp_f32_e32 v161, v161
	v_lshl_or_b32 v146, s52, 7, v151
	v_pk_add_f32 v[158:159], v[158:159], 1.0 op_sel_hi:[1,0]
	v_lshl_add_u32 v155, s22, 8, v137
	v_rcp_f32_e32 v158, v158
	v_rcp_f32_e32 v159, v159
	v_pk_add_f32 v[160:161], v[160:161], 1.0 op_sel_hi:[1,0]
	v_ashrrev_i32_e32 v147, 31, v146
	v_rcp_f32_e32 v160, v160
	v_rcp_f32_e32 v161, v161
	v_pk_mul_f32 v[124:125], v[124:125], v[158:159]
	v_pk_mul_f32 v[158:159], v[122:123], s[12:13] op_sel_hi:[1,0]
	v_pk_mul_f32 v[116:117], v[124:125], v[116:117]
	v_pk_mul_f32 v[124:125], v[126:127], v[160:161]
	v_pk_mul_f32 v[126:127], v[120:121], s[12:13] op_sel_hi:[1,0]
	v_exp_f32_e32 v158, v158
	v_exp_f32_e32 v126, v126
	v_exp_f32_e32 v127, v127
	v_exp_f32_e32 v159, v159
	v_mov_b64_e32 v[148:149], s[46:47]
	v_mad_i64_i32 v[156:157], s[24:25], v155, s51, v[148:149]
	v_pk_add_f32 v[126:127], v[126:127], 1.0 op_sel_hi:[1,0]
	v_pk_add_f32 v[158:159], v[158:159], 1.0 op_sel_hi:[1,0]
	v_rcp_f32_e32 v126, v126
	v_rcp_f32_e32 v127, v127
	v_rcp_f32_e32 v158, v158
	v_rcp_f32_e32 v159, v159
	v_lshlrev_b64 v[146:147], 1, v[146:147]
	v_pk_mul_f32 v[120:121], v[120:121], v[126:127]
	v_lshl_add_u64 v[156:157], v[156:157], 0, v[146:147]
	v_pk_mul_f32 v[120:121], v[120:121], v[112:113]
	v_pk_mul_f32 v[112:113], v[122:123], v[158:159]
	v_pk_mul_f32 v[118:119], v[124:125], v[118:119]
	v_pk_mul_f32 v[122:123], v[112:113], v[114:115]
	v_cvt_pk_bf16_f32 v112, v116, v117
	v_cvt_pk_bf16_f32 v113, v118, v119
	v_cvt_pk_bf16_f32 v114, v120, v121
	v_pk_mul_f32 v[116:117], v[110:111], s[12:13] op_sel_hi:[1,0]
	v_cvt_pk_bf16_f32 v115, v122, v123
	global_store_dwordx4 v[156:157], v[112:115], off
	v_exp_f32_e32 v116, v116
	v_exp_f32_e32 v117, v117
	v_pk_mul_f32 v[114:115], v[108:109], s[12:13] op_sel_hi:[1,0]
	v_or_b32_e32 v112, 16, v155
	v_exp_f32_e32 v114, v114
	v_exp_f32_e32 v115, v115
	v_pk_add_f32 v[116:117], v[116:117], 1.0 op_sel_hi:[1,0]
	v_mad_i64_i32 v[112:113], s[24:25], v112, s51, v[148:149]
	v_pk_add_f32 v[114:115], v[114:115], 1.0 op_sel_hi:[1,0]
	v_rcp_f32_e32 v116, v116
	v_rcp_f32_e32 v114, v114
	v_rcp_f32_e32 v115, v115
	v_rcp_f32_e32 v117, v117
	v_lshl_add_u64 v[112:113], v[112:113], 0, v[146:147]
	s_andn2_b64 vcc, exec, s[0:1]
	v_pk_mul_f32 v[108:109], v[108:109], v[114:115]
	v_pk_mul_f32 v[114:115], v[106:107], s[12:13] op_sel_hi:[1,0]
	v_pk_mul_f32 v[100:101], v[108:109], v[100:101]
	v_pk_mul_f32 v[108:109], v[110:111], v[116:117]
	v_pk_mul_f32 v[110:111], v[104:105], s[12:13] op_sel_hi:[1,0]
	v_exp_f32_e32 v114, v114
	v_exp_f32_e32 v110, v110
	v_exp_f32_e32 v111, v111
	v_exp_f32_e32 v115, v115
	v_pk_mul_f32 v[102:103], v[108:109], v[102:103]
	s_mov_b64 s[0:1], -1
	v_pk_add_f32 v[110:111], v[110:111], 1.0 op_sel_hi:[1,0]
	v_pk_add_f32 v[114:115], v[114:115], 1.0 op_sel_hi:[1,0]
	v_rcp_f32_e32 v110, v110
	v_rcp_f32_e32 v111, v111
	v_rcp_f32_e32 v114, v114
	v_rcp_f32_e32 v115, v115
	v_pk_mul_f32 v[104:105], v[104:105], v[110:111]
	s_nop 0
	v_pk_mul_f32 v[104:105], v[104:105], v[96:97]
	v_pk_mul_f32 v[96:97], v[106:107], v[114:115]
	s_nop 0
	v_pk_mul_f32 v[106:107], v[96:97], v[98:99]
	v_cvt_pk_bf16_f32 v96, v100, v101
	v_cvt_pk_bf16_f32 v97, v102, v103
	v_cvt_pk_bf16_f32 v98, v104, v105
	v_pk_mul_f32 v[100:101], v[94:95], s[12:13] op_sel_hi:[1,0]
	v_cvt_pk_bf16_f32 v99, v106, v107
	global_store_dwordx4 v[112:113], v[96:99], off
	v_exp_f32_e32 v100, v100
	v_exp_f32_e32 v101, v101
	v_pk_mul_f32 v[98:99], v[92:93], s[12:13] op_sel_hi:[1,0]
	v_or_b32_e32 v96, 32, v155
	v_exp_f32_e32 v98, v98
	v_exp_f32_e32 v99, v99
	v_pk_add_f32 v[100:101], v[100:101], 1.0 op_sel_hi:[1,0]
	v_mad_i64_i32 v[96:97], s[24:25], v96, s51, v[148:149]
	v_pk_add_f32 v[98:99], v[98:99], 1.0 op_sel_hi:[1,0]
	v_rcp_f32_e32 v100, v100
	v_rcp_f32_e32 v98, v98
	v_rcp_f32_e32 v99, v99
	v_rcp_f32_e32 v101, v101
	v_lshl_add_u64 v[96:97], v[96:97], 0, v[146:147]
	v_pk_mul_f32 v[92:93], v[92:93], v[98:99]
	s_nop 0
	v_pk_mul_f32 v[84:85], v[92:93], v[84:85]
	v_pk_mul_f32 v[92:93], v[94:95], v[100:101]
	v_pk_mul_f32 v[94:95], v[88:89], s[12:13] op_sel_hi:[1,0]
	v_pk_mul_f32 v[98:99], v[90:91], s[12:13] op_sel_hi:[1,0]
	v_exp_f32_e32 v94, v94
	v_exp_f32_e32 v95, v95
	v_exp_f32_e32 v98, v98
	v_exp_f32_e32 v99, v99
	v_pk_mul_f32 v[86:87], v[92:93], v[86:87]
	v_pk_add_f32 v[94:95], v[94:95], 1.0 op_sel_hi:[1,0]
	v_pk_add_f32 v[98:99], v[98:99], 1.0 op_sel_hi:[1,0]
	v_rcp_f32_e32 v94, v94
	v_rcp_f32_e32 v95, v95
	v_rcp_f32_e32 v98, v98
	v_rcp_f32_e32 v99, v99
	v_pk_mul_f32 v[88:89], v[88:89], v[94:95]
	s_nop 0
	v_pk_mul_f32 v[88:89], v[88:89], v[80:81]
	v_pk_mul_f32 v[80:81], v[90:91], v[98:99]
	s_nop 0
	v_pk_mul_f32 v[90:91], v[80:81], v[82:83]
	v_cvt_pk_bf16_f32 v80, v84, v85
	v_cvt_pk_bf16_f32 v81, v86, v87
	v_cvt_pk_bf16_f32 v82, v88, v89
	v_pk_mul_f32 v[84:85], v[78:79], s[12:13] op_sel_hi:[1,0]
	v_cvt_pk_bf16_f32 v83, v90, v91
	global_store_dwordx4 v[96:97], v[80:83], off
	v_exp_f32_e32 v84, v84
	v_exp_f32_e32 v85, v85
	v_pk_mul_f32 v[82:83], v[76:77], s[12:13] op_sel_hi:[1,0]
	v_or_b32_e32 v80, 48, v155
	v_exp_f32_e32 v82, v82
	v_exp_f32_e32 v83, v83
	v_pk_add_f32 v[84:85], v[84:85], 1.0 op_sel_hi:[1,0]
	v_mad_i64_i32 v[80:81], s[24:25], v80, s51, v[148:149]
	v_pk_add_f32 v[82:83], v[82:83], 1.0 op_sel_hi:[1,0]
	v_rcp_f32_e32 v84, v84
	v_rcp_f32_e32 v82, v82
	v_rcp_f32_e32 v83, v83
	v_rcp_f32_e32 v85, v85
	v_lshl_add_u64 v[80:81], v[80:81], 0, v[146:147]
	v_pk_mul_f32 v[76:77], v[76:77], v[82:83]
	s_nop 0
	v_pk_mul_f32 v[68:69], v[76:77], v[68:69]
; __device__ __forceinline__ unsigned cvt_pk_bf16(float lo, float hi) { unsigned r; asm volatile("v_cvt_pk_bf16_f32 %0, %1, %2" : "=v"(r) : "v"(lo), "v"(hi)); return r; }
; #define PG8_BAR __builtin_amdgcn_s_barrier()
;     __device__ __forceinline__ void operator()(const f32x4 (&acc)[2][2][4][2], const Unit& u, int wr, int wc, int fr, int fq) const {
;     ...
;             for (int m = 0; m < 4; ++m) {
;                 bf16_t* rowp = O + (size_t)(row0 + ai * HALF + m * 16) * ldc + col0;
;                 const f32x4 g0 = acc[ai][0][m][0], g1 = acc[ai][0][m][1], u0 = acc[ai][1][m][0], u1 = acc[ai][1][m][1];
;                 const f32x2 a = silu_mul_pk((f32x2){g0[0], g0[1]}, (f32x2){u0[0], u0[1]}), b = silu_mul_pk((f32x2){g0[2], g0[3]}, (f32x2){u0[2], u0[3]});
;                 const f32x2 c = silu_mul_pk((f32x2){g1[0], g1[1]}, (f32x2){u1[0], u1[1]}), d = silu_mul_pk((f32x2){g1[2], g1[3]}, (f32x2){u1[2], u1[3]});
;                 u32x4 w; w.x = cvt_pk_bf16(a.x, a.y); w.y = cvt_pk_bf16(b.x, b.y); w.z = cvt_pk_bf16(c.x, c.y); w.w = cvt_pk_bf16(d.x, d.y);
;                 *(u32x4*)rowp = w;
;             }
; template <class Epi, bool ALIGN_EPI, class Hook = NoHook>
; __device__ __forceinline__ void gemm_phase(LAS unsigned char* lds, const Gemm g, const StaticOrder& S, const Epi& E, const Hook& HK = Hook()) {
;     ...
;         E(acc, cur, wr, wc, fr, fq);
;         if (!has_next) break;
; #pragma unroll
;         for (int a = 0; a < 2; ++a)
; #pragma unroll
;             for (int b = 0; b < 2; ++b)
; #pragma unroll
;                 for (int m = 0; m < 4; ++m)
; #pragma unroll
;                     for (int n = 0; n < 2; ++n) acc[a][b][m][n] = (f32x4){0.f, 0.f, 0.f, 0.f};
;         cur = nxt; cA = nA; cB = nB; ++ui;
;         if constexpr (ALIGN_EPI) { if (wr == 1) PG8_BAR; }
	v_pk_mul_f32 v[76:77], v[78:79], v[84:85]
	v_pk_mul_f32 v[78:79], v[72:73], s[12:13] op_sel_hi:[1,0]
	v_pk_mul_f32 v[82:83], v[74:75], s[12:13] op_sel_hi:[1,0]
	v_exp_f32_e32 v78, v78
	v_exp_f32_e32 v79, v79
	v_exp_f32_e32 v82, v82
	v_exp_f32_e32 v83, v83
	v_pk_mul_f32 v[70:71], v[76:77], v[70:71]
	v_pk_add_f32 v[78:79], v[78:79], 1.0 op_sel_hi:[1,0]
	v_pk_add_f32 v[82:83], v[82:83], 1.0 op_sel_hi:[1,0]
	v_rcp_f32_e32 v78, v78
	v_rcp_f32_e32 v79, v79
	v_rcp_f32_e32 v82, v82
	v_rcp_f32_e32 v83, v83
	v_pk_mul_f32 v[72:73], v[72:73], v[78:79]
	s_nop 0
	v_pk_mul_f32 v[72:73], v[72:73], v[64:65]
	v_pk_mul_f32 v[64:65], v[74:75], v[82:83]
	s_nop 0
	v_pk_mul_f32 v[74:75], v[64:65], v[66:67]
	v_cvt_pk_bf16_f32 v64, v68, v69
	v_cvt_pk_bf16_f32 v65, v70, v71
	v_cvt_pk_bf16_f32 v66, v72, v73
	v_pk_mul_f32 v[68:69], v[62:63], s[12:13] op_sel_hi:[1,0]
	v_cvt_pk_bf16_f32 v67, v74, v75
	global_store_dwordx4 v[80:81], v[64:67], off
	v_exp_f32_e32 v68, v68
	v_exp_f32_e32 v69, v69
	v_pk_mul_f32 v[66:67], v[60:61], s[12:13] op_sel_hi:[1,0]
	v_add_u32_e32 v64, 0x80, v155
	v_exp_f32_e32 v66, v66
	v_exp_f32_e32 v67, v67
	v_pk_add_f32 v[68:69], v[68:69], 1.0 op_sel_hi:[1,0]
	v_mad_i64_i32 v[64:65], s[24:25], v64, s51, v[148:149]
	v_pk_add_f32 v[66:67], v[66:67], 1.0 op_sel_hi:[1,0]
	v_rcp_f32_e32 v68, v68
	v_rcp_f32_e32 v66, v66
	v_rcp_f32_e32 v67, v67
	v_rcp_f32_e32 v69, v69
	v_lshl_add_u64 v[64:65], v[64:65], 0, v[146:147]
	v_pk_mul_f32 v[60:61], v[60:61], v[66:67]
	s_nop 0
	v_pk_mul_f32 v[52:53], v[60:61], v[52:53]
	v_pk_mul_f32 v[60:61], v[62:63], v[68:69]
	v_pk_mul_f32 v[62:63], v[56:57], s[12:13] op_sel_hi:[1,0]
	v_pk_mul_f32 v[66:67], v[58:59], s[12:13] op_sel_hi:[1,0]
	v_exp_f32_e32 v62, v62
	v_exp_f32_e32 v63, v63
	v_exp_f32_e32 v66, v66
	v_exp_f32_e32 v67, v67
	v_pk_mul_f32 v[54:55], v[60:61], v[54:55]
	v_pk_add_f32 v[62:63], v[62:63], 1.0 op_sel_hi:[1,0]
	v_pk_add_f32 v[66:67], v[66:67], 1.0 op_sel_hi:[1,0]
	v_rcp_f32_e32 v62, v62
	v_rcp_f32_e32 v63, v63
	v_rcp_f32_e32 v66, v66
	v_rcp_f32_e32 v67, v67
	v_pk_mul_f32 v[56:57], v[56:57], v[62:63]
	s_nop 0
	v_pk_mul_f32 v[56:57], v[56:57], v[48:49]
	v_pk_mul_f32 v[48:49], v[58:59], v[66:67]
	s_nop 0
	v_pk_mul_f32 v[58:59], v[48:49], v[50:51]
	v_cvt_pk_bf16_f32 v48, v52, v53
	v_cvt_pk_bf16_f32 v49, v54, v55
	v_cvt_pk_bf16_f32 v50, v56, v57
	v_pk_mul_f32 v[52:53], v[46:47], s[12:13] op_sel_hi:[1,0]
	v_cvt_pk_bf16_f32 v51, v58, v59
	global_store_dwordx4 v[64:65], v[48:51], off
	v_exp_f32_e32 v52, v52
	v_exp_f32_e32 v53, v53
	v_pk_mul_f32 v[50:51], v[44:45], s[12:13] op_sel_hi:[1,0]
	v_add_u32_e32 v48, 0x90, v155
	v_exp_f32_e32 v50, v50
	v_exp_f32_e32 v51, v51
	v_pk_add_f32 v[52:53], v[52:53], 1.0 op_sel_hi:[1,0]
	v_mad_i64_i32 v[48:49], s[24:25], v48, s51, v[148:149]
	v_pk_add_f32 v[50:51], v[50:51], 1.0 op_sel_hi:[1,0]
	v_rcp_f32_e32 v52, v52
	v_rcp_f32_e32 v50, v50
	v_rcp_f32_e32 v51, v51
	v_rcp_f32_e32 v53, v53
	v_lshl_add_u64 v[48:49], v[48:49], 0, v[146:147]
	v_pk_mul_f32 v[44:45], v[44:45], v[50:51]
	s_nop 0
	v_pk_mul_f32 v[36:37], v[44:45], v[36:37]
	v_pk_mul_f32 v[44:45], v[46:47], v[52:53]
	v_pk_mul_f32 v[46:47], v[40:41], s[12:13] op_sel_hi:[1,0]
	v_pk_mul_f32 v[50:51], v[42:43], s[12:13] op_sel_hi:[1,0]
	v_exp_f32_e32 v46, v46
	v_exp_f32_e32 v47, v47
	v_exp_f32_e32 v50, v50
	v_exp_f32_e32 v51, v51
	v_pk_mul_f32 v[38:39], v[44:45], v[38:39]
	v_pk_add_f32 v[46:47], v[46:47], 1.0 op_sel_hi:[1,0]
	v_pk_add_f32 v[50:51], v[50:51], 1.0 op_sel_hi:[1,0]
	v_rcp_f32_e32 v46, v46
	v_rcp_f32_e32 v47, v47
	v_rcp_f32_e32 v50, v50
	v_rcp_f32_e32 v51, v51
	v_pk_mul_f32 v[40:41], v[40:41], v[46:47]
	s_nop 0
	v_pk_mul_f32 v[40:41], v[40:41], v[32:33]
	v_pk_mul_f32 v[32:33], v[42:43], v[50:51]
	s_nop 0
	v_pk_mul_f32 v[42:43], v[32:33], v[34:35]
	v_cvt_pk_bf16_f32 v32, v36, v37
	v_cvt_pk_bf16_f32 v33, v38, v39
	v_cvt_pk_bf16_f32 v34, v40, v41
	v_pk_mul_f32 v[36:37], v[30:31], s[12:13] op_sel_hi:[1,0]
	v_cvt_pk_bf16_f32 v35, v42, v43
	global_store_dwordx4 v[48:49], v[32:35], off
	v_exp_f32_e32 v36, v36
	v_exp_f32_e32 v37, v37
	v_pk_mul_f32 v[34:35], v[28:29], s[12:13] op_sel_hi:[1,0]
	v_add_u32_e32 v32, 0xa0, v155
	v_exp_f32_e32 v34, v34
	v_exp_f32_e32 v35, v35
	v_pk_add_f32 v[36:37], v[36:37], 1.0 op_sel_hi:[1,0]
	v_mad_i64_i32 v[32:33], s[24:25], v32, s51, v[148:149]
	v_pk_add_f32 v[34:35], v[34:35], 1.0 op_sel_hi:[1,0]
	v_rcp_f32_e32 v36, v36
	v_rcp_f32_e32 v34, v34
	v_rcp_f32_e32 v35, v35
	v_rcp_f32_e32 v37, v37
	v_lshl_add_u64 v[32:33], v[32:33], 0, v[146:147]
	v_pk_mul_f32 v[28:29], v[28:29], v[34:35]
	s_nop 0
	v_pk_mul_f32 v[20:21], v[28:29], v[20:21]
	v_pk_mul_f32 v[28:29], v[30:31], v[36:37]
	v_pk_mul_f32 v[30:31], v[24:25], s[12:13] op_sel_hi:[1,0]
	v_pk_mul_f32 v[34:35], v[26:27], s[12:13] op_sel_hi:[1,0]
	v_exp_f32_e32 v30, v30
	v_exp_f32_e32 v31, v31
	v_exp_f32_e32 v34, v34
	v_exp_f32_e32 v35, v35
	v_pk_mul_f32 v[22:23], v[28:29], v[22:23]
	v_pk_add_f32 v[30:31], v[30:31], 1.0 op_sel_hi:[1,0]
	v_pk_add_f32 v[34:35], v[34:35], 1.0 op_sel_hi:[1,0]
	v_rcp_f32_e32 v30, v30
	v_rcp_f32_e32 v31, v31
	v_rcp_f32_e32 v34, v34
	v_rcp_f32_e32 v35, v35
	v_pk_mul_f32 v[24:25], v[24:25], v[30:31]
	s_nop 0
	v_pk_mul_f32 v[24:25], v[24:25], v[16:17]
	v_pk_mul_f32 v[16:17], v[26:27], v[34:35]
	s_nop 0
	v_pk_mul_f32 v[26:27], v[16:17], v[18:19]
	v_cvt_pk_bf16_f32 v16, v20, v21
	v_cvt_pk_bf16_f32 v17, v22, v23
	v_cvt_pk_bf16_f32 v18, v24, v25
	v_pk_mul_f32 v[20:21], v[14:15], s[12:13] op_sel_hi:[1,0]
	v_cvt_pk_bf16_f32 v19, v26, v27
	global_store_dwordx4 v[32:33], v[16:19], off
	v_exp_f32_e32 v20, v20
	v_exp_f32_e32 v21, v21
	v_pk_mul_f32 v[18:19], v[12:13], s[12:13] op_sel_hi:[1,0]
	v_add_u32_e32 v16, 0xb0, v155
	v_exp_f32_e32 v18, v18
	v_exp_f32_e32 v19, v19
	v_pk_add_f32 v[20:21], v[20:21], 1.0 op_sel_hi:[1,0]
	v_mad_i64_i32 v[16:17], s[24:25], v16, s51, v[148:149]
	v_pk_add_f32 v[18:19], v[18:19], 1.0 op_sel_hi:[1,0]
	v_rcp_f32_e32 v20, v20
	v_rcp_f32_e32 v18, v18
	v_rcp_f32_e32 v19, v19
	v_rcp_f32_e32 v21, v21
	v_lshl_add_u64 v[16:17], v[16:17], 0, v[146:147]
	v_pk_mul_f32 v[12:13], v[12:13], v[18:19]
	s_nop 0
	v_pk_mul_f32 v[4:5], v[12:13], v[4:5]
	v_pk_mul_f32 v[12:13], v[14:15], v[20:21]
	v_pk_mul_f32 v[14:15], v[8:9], s[12:13] op_sel_hi:[1,0]
	v_pk_mul_f32 v[18:19], v[10:11], s[12:13] op_sel_hi:[1,0]
	v_exp_f32_e32 v14, v14
	v_exp_f32_e32 v15, v15
	v_exp_f32_e32 v18, v18
	v_exp_f32_e32 v19, v19
	v_pk_mul_f32 v[6:7], v[12:13], v[6:7]
	v_pk_add_f32 v[14:15], v[14:15], 1.0 op_sel_hi:[1,0]
	v_pk_add_f32 v[18:19], v[18:19], 1.0 op_sel_hi:[1,0]
	v_rcp_f32_e32 v14, v14
	v_rcp_f32_e32 v15, v15
	v_rcp_f32_e32 v18, v18
	v_rcp_f32_e32 v19, v19
	v_pk_mul_f32 v[8:9], v[8:9], v[14:15]
	s_nop 0
	v_pk_mul_f32 v[8:9], v[8:9], v[0:1]
	v_pk_mul_f32 v[0:1], v[10:11], v[18:19]
	s_nop 0
	v_pk_mul_f32 v[10:11], v[0:1], v[2:3]
	v_cvt_pk_bf16_f32 v0, v4, v5
	v_cvt_pk_bf16_f32 v1, v6, v7
	v_cvt_pk_bf16_f32 v2, v8, v9
	s_nop 0
	v_cvt_pk_bf16_f32 v3, v10, v11
	global_store_dwordx4 v[16:17], v[0:3], off
	s_cbranch_vccnz .LBB0_915
	s_andn2_b64 vcc, exec, s[6:7]
	s_cbranch_vccnz .LBB0_914
	s_branch .LBB0_914
; #define PG8_WAIT_V(n) asm volatile("s_waitcnt vmcnt(" #n ")" ::: "memory")
; #define PG8_BAR __builtin_amdgcn_s_barrier()
; template <class Epi, bool ALIGN_EPI, class Hook = NoHook>
; __device__ __forceinline__ void gemm_phase(LAS unsigned char* lds, const Gemm g, const StaticOrder& S, const Epi& E, const Hook& HK = Hook()) {
;     ...
;     PG8_WAIT_V(0);
;     if constexpr (!ALIGN_EPI) { if (wr == 0) PG8_BAR; }
;     PG8_BAR;
.LBB0_925:
	s_cmp_lg_u64 s[10:11], 0
	s_cbranch_scc0 .Lnoalign_skip_P10
	s_barrier

; __device__ __forceinline__ unsigned cvt_pk_bf16(float lo, float hi) { unsigned r; asm volatile("v_cvt_pk_bf16_f32 %0, %1, %2" : "=v"(r) : "v"(lo), "v"(hi)); return r; }
;     __device__ __forceinline__ void operator()(const f32x4 (&acc)[2][2][4][2], const Unit& u, int wr, int wc, int fr, int fq) const {
;         const int row0 = u.pm * BM + wr * 64 + fr; const int col0 = u.pn * BM + wc * 32 + 8 * fq;
; #pragma unroll
;         for (int ai = 0; ai < 2; ++ai) {
;             f32x4 p0[4][2], p1[4][2];
; #pragma unroll
;             for (int m = 0; m < 4; ++m)
; #pragma unroll
;                 for (int bj = 0; bj < 2; ++bj) {
;                     const size_t e = (size_t)(row0 + ai * HALF + m * 16) * 2048 + col0 + bj * HALF;
;                     if (IN_F32) { p0[m][bj] = *(const f32x4*)((const float*)base + e); p1[m][bj] = *(const f32x4*)((const float*)base + e + 4); }
;                     else { const u32x4 w = *(const u32x4*)((const bf16_t*)base + e); p0[m][bj] = (f32x4){bflo(w.x), bfhi(w.x), bflo(w.y), bfhi(w.y)}; p1[m][bj] = (f32x4){bflo(w.z), bfhi(w.z), bflo(w.w), bfhi(w.w)}; }
;                 }
; #pragma unroll
;             for (int m = 0; m < 4; ++m)
; #pragma unroll
;                 for (int bj = 0; bj < 2; ++bj) {
;                     const size_t e = (size_t)(row0 + ai * HALF + m * 16) * 2048 + col0 + bj * HALF;
;                     const f32x4 v0 = p0[m][bj] + acc[ai][bj][m][0] * scale, v1 = p1[m][bj] + acc[ai][bj][m][1] * scale;
;                     if (OUT_F32) { *(f32x4*)((float*)out + e) = v0; *(f32x4*)((float*)out + e + 4) = v1; }
;                     else { u32x4 w; w.x = cvt_pk_bf16(v0[0], v0[1]); w.y = cvt_pk_bf16(v0[2], v0[3]); w.z = cvt_pk_bf16(v1[0], v1[1]); w.w = cvt_pk_bf16(v1[2], v1[3]); *(u32x4*)((bf16_t*)out + e) = w; }
;                 }
.LBB0_1002:
	v_lshl_add_u32 v146, s39, 8, v150
	v_lshl_or_b32 v188, s40, 8, v152
	v_ashrrev_i32_e32 v189, 31, v188
	v_ashrrev_i32_e32 v147, 31, v146
	v_lshl_add_u64 v[144:145], v[188:189], 1, s[76:77]
	v_lshlrev_b64 v[148:149], 12, v[146:147]
	v_lshl_add_u64 v[148:149], v[144:145], 0, v[148:149]
	v_or_b32_e32 v190, 16, v146
	global_load_dwordx4 v[156:159], v[148:149], off
	global_load_dwordx4 v[160:163], v[148:149], off offset:256
	v_ashrrev_i32_e32 v191, 31, v190
	v_lshlrev_b64 v[148:149], 12, v[190:191]
	v_or_b32_e32 v192, 32, v146
	v_lshl_add_u64 v[148:149], v[144:145], 0, v[148:149]
	v_ashrrev_i32_e32 v193, 31, v192
	global_load_dwordx4 v[164:167], v[148:149], off
	global_load_dwordx4 v[168:171], v[148:149], off offset:256
	v_lshlrev_b64 v[148:149], 12, v[192:193]
	v_lshl_add_u64 v[148:149], v[144:145], 0, v[148:149]
	global_load_dwordx4 v[172:175], v[148:149], off
	global_load_dwordx4 v[176:179], v[148:149], off offset:256
	v_or_b32_e32 v148, 48, v146
	v_ashrrev_i32_e32 v149, 31, v148
	v_lshlrev_b64 v[180:181], 12, v[148:149]
	v_lshl_add_u64 v[184:185], v[144:145], 0, v[180:181]
	global_load_dwordx4 v[180:183], v[184:185], off
	s_nop 0
	global_load_dwordx4 v[184:187], v[184:185], off offset:256
	s_and_b64 vcc, exec, s[0:1]
	s_mov_b64 s[0:1], -1
	s_waitcnt vmcnt(0)
	v_lshlrev_b32_e32 v194, 16, v156
	v_and_b32_e32 v195, 0xffff0000, v156
	v_lshlrev_b32_e32 v156, 16, v157
	v_and_b32_e32 v157, 0xffff0000, v157
	v_lshlrev_b32_e32 v196, 16, v158
	v_and_b32_e32 v197, 0xffff0000, v158
	v_lshlrev_b32_e32 v158, 16, v159
	v_and_b32_e32 v159, 0xffff0000, v159
	v_pk_fma_f32 v[126:127], v[126:127], 0.5, v[156:157] op_sel_hi:[1,0,1]
	v_pk_fma_f32 v[156:157], v[120:121], 0.5, v[196:197] op_sel_hi:[1,0,1]
	v_lshlrev_b64 v[120:121], 13, v[146:147]
	v_lshlrev_b32_e32 v198, 16, v160
	v_and_b32_e32 v199, 0xffff0000, v160
	v_lshlrev_b32_e32 v160, 16, v161
	v_and_b32_e32 v161, 0xffff0000, v161
	v_lshlrev_b32_e32 v200, 16, v162
	v_and_b32_e32 v201, 0xffff0000, v162
	v_pk_fma_f32 v[158:159], v[122:123], 0.5, v[158:159] op_sel_hi:[1,0,1]
	v_lshl_add_u64 v[122:123], s[60:61], 0, v[120:121]
	v_lshlrev_b64 v[120:121], 2, v[188:189]
	v_lshlrev_b32_e32 v162, 16, v163
	v_and_b32_e32 v163, 0xffff0000, v163
	v_lshlrev_b32_e32 v202, 16, v164
	v_and_b32_e32 v203, 0xffff0000, v164
	v_pk_fma_f32 v[124:125], v[124:125], 0.5, v[194:195] op_sel_hi:[1,0,1]
	v_lshl_add_u64 v[122:123], v[122:123], 0, v[120:121]
	v_pk_fma_f32 v[118:119], v[118:119], 0.5, v[160:161] op_sel_hi:[1,0,1]
	v_pk_fma_f32 v[116:117], v[116:117], 0.5, v[198:199] op_sel_hi:[1,0,1]
	v_pk_fma_f32 v[108:109], v[108:109], 0.5, v[200:201] op_sel_hi:[1,0,1]
	global_store_dwordx4 v[122:123], v[124:127], off
	global_store_dwordx4 v[122:123], v[156:159], off offset:16
	v_pk_fma_f32 v[110:111], v[110:111], 0.5, v[162:163] op_sel_hi:[1,0,1]
	global_store_dwordx4 v[122:123], v[116:119], off offset:512
	global_store_dwordx4 v[122:123], v[108:111], off offset:528
	v_lshlrev_b32_e32 v164, 16, v165
	v_and_b32_e32 v165, 0xffff0000, v165
	v_pk_fma_f32 v[108:109], v[112:113], 0.5, v[202:203] op_sel_hi:[1,0,1]
	v_lshlrev_b64 v[112:113], 13, v[190:191]
	v_lshlrev_b32_e32 v206, 16, v168
	v_and_b32_e32 v207, 0xffff0000, v168
	v_lshlrev_b32_e32 v168, 16, v169
	v_and_b32_e32 v169, 0xffff0000, v169
	v_lshlrev_b32_e32 v208, 16, v170
	v_and_b32_e32 v209, 0xffff0000, v170
	v_lshl_add_u64 v[112:113], s[60:61], 0, v[112:113]
	v_lshlrev_b32_e32 v204, 16, v166
	v_and_b32_e32 v205, 0xffff0000, v166
	v_lshlrev_b32_e32 v166, 16, v167
	v_and_b32_e32 v167, 0xffff0000, v167
	v_lshlrev_b32_e32 v170, 16, v171
	v_and_b32_e32 v171, 0xffff0000, v171
	v_lshlrev_b32_e32 v210, 16, v172
	v_and_b32_e32 v211, 0xffff0000, v172
	v_pk_fma_f32 v[110:111], v[114:115], 0.5, v[164:165] op_sel_hi:[1,0,1]
	v_lshl_add_u64 v[112:113], v[112:113], 0, v[120:121]
	v_pk_fma_f32 v[102:103], v[102:103], 0.5, v[168:169] op_sel_hi:[1,0,1]
	v_pk_fma_f32 v[100:101], v[100:101], 0.5, v[206:207] op_sel_hi:[1,0,1]
	v_pk_fma_f32 v[92:93], v[92:93], 0.5, v[208:209] op_sel_hi:[1,0,1]
	v_pk_fma_f32 v[106:107], v[106:107], 0.5, v[166:167] op_sel_hi:[1,0,1]
	v_pk_fma_f32 v[104:105], v[104:105], 0.5, v[204:205] op_sel_hi:[1,0,1]
	global_store_dwordx4 v[112:113], v[108:111], off
	global_store_dwordx4 v[112:113], v[104:107], off offset:16
	v_pk_fma_f32 v[94:95], v[94:95], 0.5, v[170:171] op_sel_hi:[1,0,1]
	global_store_dwordx4 v[112:113], v[100:103], off offset:512
	global_store_dwordx4 v[112:113], v[92:95], off offset:528
	v_lshlrev_b32_e32 v172, 16, v173
	v_and_b32_e32 v173, 0xffff0000, v173
	v_pk_fma_f32 v[92:93], v[96:97], 0.5, v[210:211] op_sel_hi:[1,0,1]
	v_lshlrev_b64 v[96:97], 13, v[192:193]
	v_lshlrev_b32_e32 v214, 16, v176
	v_and_b32_e32 v215, 0xffff0000, v176
	v_lshlrev_b32_e32 v176, 16, v177
	v_and_b32_e32 v177, 0xffff0000, v177
	v_lshlrev_b32_e32 v216, 16, v178
	v_and_b32_e32 v217, 0xffff0000, v178
	v_lshl_add_u64 v[96:97], s[60:61], 0, v[96:97]
	v_lshlrev_b32_e32 v212, 16, v174
	v_and_b32_e32 v213, 0xffff0000, v174
	v_lshlrev_b32_e32 v174, 16, v175
	v_and_b32_e32 v175, 0xffff0000, v175
	v_lshlrev_b32_e32 v178, 16, v179
	v_and_b32_e32 v179, 0xffff0000, v179
	v_lshlrev_b32_e32 v218, 16, v180
	v_and_b32_e32 v219, 0xffff0000, v180
	v_pk_fma_f32 v[94:95], v[98:99], 0.5, v[172:173] op_sel_hi:[1,0,1]
	v_lshl_add_u64 v[96:97], v[96:97], 0, v[120:121]
	v_pk_fma_f32 v[86:87], v[86:87], 0.5, v[176:177] op_sel_hi:[1,0,1]
	v_pk_fma_f32 v[84:85], v[84:85], 0.5, v[214:215] op_sel_hi:[1,0,1]
	v_pk_fma_f32 v[76:77], v[76:77], 0.5, v[216:217] op_sel_hi:[1,0,1]
	v_pk_fma_f32 v[90:91], v[90:91], 0.5, v[174:175] op_sel_hi:[1,0,1]
	v_pk_fma_f32 v[88:89], v[88:89], 0.5, v[212:213] op_sel_hi:[1,0,1]
; __device__ __forceinline__ unsigned cvt_pk_bf16(float lo, float hi) { unsigned r; asm volatile("v_cvt_pk_bf16_f32 %0, %1, %2" : "=v"(r) : "v"(lo), "v"(hi)); return r; }
;     __device__ __forceinline__ void operator()(const f32x4 (&acc)[2][2][4][2], const Unit& u, int wr, int wc, int fr, int fq) const {
;     ...
;         for (int ai = 0; ai < 2; ++ai) {
;             f32x4 p0[4][2], p1[4][2];
; #pragma unroll
;             for (int m = 0; m < 4; ++m)
; #pragma unroll
;                 for (int bj = 0; bj < 2; ++bj) {
;                     const size_t e = (size_t)(row0 + ai * HALF + m * 16) * 2048 + col0 + bj * HALF;
;                     if (IN_F32) { p0[m][bj] = *(const f32x4*)((const float*)base + e); p1[m][bj] = *(const f32x4*)((const float*)base + e + 4); }
;                     else { const u32x4 w = *(const u32x4*)((const bf16_t*)base + e); p0[m][bj] = (f32x4){bflo(w.x), bfhi(w.x), bflo(w.y), bfhi(w.y)}; p1[m][bj] = (f32x4){bflo(w.z), bfhi(w.z), bflo(w.w), bfhi(w.w)}; }
;                 }
; #pragma unroll
;             for (int m = 0; m < 4; ++m)
; #pragma unroll
;                 for (int bj = 0; bj < 2; ++bj) {
;                     const size_t e = (size_t)(row0 + ai * HALF + m * 16) * 2048 + col0 + bj * HALF;
;                     const f32x4 v0 = p0[m][bj] + acc[ai][bj][m][0] * scale, v1 = p1[m][bj] + acc[ai][bj][m][1] * scale;
;                     if (OUT_F32) { *(f32x4*)((float*)out + e) = v0; *(f32x4*)((float*)out + e + 4) = v1; }
;                     else { u32x4 w; w.x = cvt_pk_bf16(v0[0], v0[1]); w.y = cvt_pk_bf16(v0[2], v0[3]); w.z = cvt_pk_bf16(v1[0], v1[1]); w.w = cvt_pk_bf16(v1[2], v1[3]); *(u32x4*)((bf16_t*)out + e) = w; }
;                 }
	global_store_dwordx4 v[96:97], v[92:95], off
	global_store_dwordx4 v[96:97], v[88:91], off offset:16
	v_pk_fma_f32 v[78:79], v[78:79], 0.5, v[178:179] op_sel_hi:[1,0,1]
	global_store_dwordx4 v[96:97], v[84:87], off offset:512
	global_store_dwordx4 v[96:97], v[76:79], off offset:528
	v_lshlrev_b32_e32 v180, 16, v181
	v_and_b32_e32 v181, 0xffff0000, v181
	v_pk_fma_f32 v[76:77], v[80:81], 0.5, v[218:219] op_sel_hi:[1,0,1]
	v_lshlrev_b64 v[80:81], 13, v[148:149]
	v_lshlrev_b32_e32 v222, 16, v184
	v_and_b32_e32 v223, 0xffff0000, v184
	v_lshlrev_b32_e32 v184, 16, v185
	v_and_b32_e32 v185, 0xffff0000, v185
	v_lshlrev_b32_e32 v224, 16, v186
	v_and_b32_e32 v225, 0xffff0000, v186
	v_lshl_add_u64 v[80:81], s[60:61], 0, v[80:81]
	v_add_u32_e32 v98, 0x80, v146
	v_lshlrev_b32_e32 v220, 16, v182
	v_and_b32_e32 v221, 0xffff0000, v182
	v_lshlrev_b32_e32 v182, 16, v183
	v_and_b32_e32 v183, 0xffff0000, v183
	v_lshlrev_b32_e32 v186, 16, v187
	v_and_b32_e32 v187, 0xffff0000, v187
	v_pk_fma_f32 v[78:79], v[82:83], 0.5, v[180:181] op_sel_hi:[1,0,1]
	v_lshl_add_u64 v[80:81], v[80:81], 0, v[120:121]
	v_pk_fma_f32 v[70:71], v[70:71], 0.5, v[184:185] op_sel_hi:[1,0,1]
	v_pk_fma_f32 v[68:69], v[68:69], 0.5, v[222:223] op_sel_hi:[1,0,1]
	v_pk_fma_f32 v[64:65], v[64:65], 0.5, v[224:225] op_sel_hi:[1,0,1]
	v_ashrrev_i32_e32 v99, 31, v98
	v_pk_fma_f32 v[74:75], v[74:75], 0.5, v[182:183] op_sel_hi:[1,0,1]
	v_pk_fma_f32 v[72:73], v[72:73], 0.5, v[220:221] op_sel_hi:[1,0,1]
	global_store_dwordx4 v[80:81], v[76:79], off
	global_store_dwordx4 v[80:81], v[72:75], off offset:16
	v_pk_fma_f32 v[66:67], v[66:67], 0.5, v[186:187] op_sel_hi:[1,0,1]
	global_store_dwordx4 v[80:81], v[68:71], off offset:512
	global_store_dwordx4 v[80:81], v[64:67], off offset:528
	v_add_u32_e32 v100, 0x90, v146
	v_ashrrev_i32_e32 v101, 31, v100
	v_lshlrev_b64 v[64:65], 12, v[98:99]
	v_lshl_add_u64 v[64:65], v[144:145], 0, v[64:65]
	global_load_dwordx4 v[66:69], v[64:65], off
	global_load_dwordx4 v[70:73], v[64:65], off offset:256
	v_lshlrev_b64 v[64:65], 12, v[100:101]
	v_add_u32_e32 v102, 0xa0, v146
	v_lshl_add_u64 v[64:65], v[144:145], 0, v[64:65]
	v_ashrrev_i32_e32 v103, 31, v102
	global_load_dwordx4 v[74:77], v[64:65], off
	global_load_dwordx4 v[78:81], v[64:65], off offset:256
	v_lshlrev_b64 v[64:65], 12, v[102:103]
	v_lshl_add_u64 v[64:65], v[144:145], 0, v[64:65]
	global_load_dwordx4 v[82:85], v[64:65], off
	global_load_dwordx4 v[86:89], v[64:65], off offset:256
	v_add_u32_e32 v64, 0xb0, v146
	v_ashrrev_i32_e32 v65, 31, v64
	v_lshlrev_b64 v[90:91], 12, v[64:65]
	v_lshl_add_u64 v[94:95], v[144:145], 0, v[90:91]
	global_load_dwordx4 v[90:93], v[94:95], off
	s_nop 0
	global_load_dwordx4 v[94:97], v[94:95], off offset:256
	s_waitcnt vmcnt(7)
	v_lshlrev_b32_e32 v104, 16, v66
	v_and_b32_e32 v105, 0xffff0000, v66
	v_lshlrev_b32_e32 v66, 16, v67
	v_and_b32_e32 v67, 0xffff0000, v67
	v_pk_fma_f32 v[62:63], v[62:63], 0.5, v[66:67] op_sel_hi:[1,0,1]
	v_lshlrev_b64 v[66:67], 13, v[98:99]
	s_waitcnt vmcnt(6)
	v_lshlrev_b32_e32 v108, 16, v70
	v_and_b32_e32 v109, 0xffff0000, v70
	v_lshlrev_b32_e32 v70, 16, v71
	v_and_b32_e32 v71, 0xffff0000, v71
	v_lshlrev_b32_e32 v110, 16, v72
	v_and_b32_e32 v111, 0xffff0000, v72
	v_lshl_add_u64 v[66:67], s[60:61], 0, v[66:67]
	v_lshlrev_b32_e32 v106, 16, v68
	v_and_b32_e32 v107, 0xffff0000, v68
	v_lshlrev_b32_e32 v68, 16, v69
	v_and_b32_e32 v69, 0xffff0000, v69
	v_lshlrev_b32_e32 v72, 16, v73
	v_and_b32_e32 v73, 0xffff0000, v73
	s_waitcnt vmcnt(5)
	v_lshlrev_b32_e32 v112, 16, v74
	v_and_b32_e32 v113, 0xffff0000, v74
	v_pk_fma_f32 v[60:61], v[60:61], 0.5, v[104:105] op_sel_hi:[1,0,1]
	v_lshl_add_u64 v[66:67], v[66:67], 0, v[120:121]
	v_pk_fma_f32 v[54:55], v[54:55], 0.5, v[70:71] op_sel_hi:[1,0,1]
	v_pk_fma_f32 v[52:53], v[52:53], 0.5, v[108:109] op_sel_hi:[1,0,1]
	v_pk_fma_f32 v[44:45], v[44:45], 0.5, v[110:111] op_sel_hi:[1,0,1]
	v_pk_fma_f32 v[58:59], v[58:59], 0.5, v[68:69] op_sel_hi:[1,0,1]
	v_pk_fma_f32 v[56:57], v[56:57], 0.5, v[106:107] op_sel_hi:[1,0,1]
	global_store_dwordx4 v[66:67], v[60:63], off
	global_store_dwordx4 v[66:67], v[56:59], off offset:16
	v_pk_fma_f32 v[46:47], v[46:47], 0.5, v[72:73] op_sel_hi:[1,0,1]
	global_store_dwordx4 v[66:67], v[52:55], off offset:512
	global_store_dwordx4 v[66:67], v[44:47], off offset:528
	v_lshlrev_b32_e32 v74, 16, v75
	v_and_b32_e32 v75, 0xffff0000, v75
	v_pk_fma_f32 v[44:45], v[48:49], 0.5, v[112:113] op_sel_hi:[1,0,1]
	v_lshlrev_b64 v[48:49], 13, v[100:101]
	s_waitcnt vmcnt(8)
; __device__ __forceinline__ unsigned cvt_pk_bf16(float lo, float hi) { unsigned r; asm volatile("v_cvt_pk_bf16_f32 %0, %1, %2" : "=v"(r) : "v"(lo), "v"(hi)); return r; }
; #define PG8_BAR __builtin_amdgcn_s_barrier()
;     __device__ __forceinline__ void operator()(const f32x4 (&acc)[2][2][4][2], const Unit& u, int wr, int wc, int fr, int fq) const {
;     ...
;         for (int ai = 0; ai < 2; ++ai) {
;             f32x4 p0[4][2], p1[4][2];
; #pragma unroll
;             for (int m = 0; m < 4; ++m)
; #pragma unroll
;                 for (int bj = 0; bj < 2; ++bj) {
;                     const size_t e = (size_t)(row0 + ai * HALF + m * 16) * 2048 + col0 + bj * HALF;
;                     if (IN_F32) { p0[m][bj] = *(const f32x4*)((const float*)base + e); p1[m][bj] = *(const f32x4*)((const float*)base + e + 4); }
;                     else { const u32x4 w = *(const u32x4*)((const bf16_t*)base + e); p0[m][bj] = (f32x4){bflo(w.x), bfhi(w.x), bflo(w.y), bfhi(w.y)}; p1[m][bj] = (f32x4){bflo(w.z), bfhi(w.z), bflo(w.w), bfhi(w.w)}; }
;                 }
; #pragma unroll
;             for (int m = 0; m < 4; ++m)
; #pragma unroll
;                 for (int bj = 0; bj < 2; ++bj) {
;                     const size_t e = (size_t)(row0 + ai * HALF + m * 16) * 2048 + col0 + bj * HALF;
;                     const f32x4 v0 = p0[m][bj] + acc[ai][bj][m][0] * scale, v1 = p1[m][bj] + acc[ai][bj][m][1] * scale;
;                     if (OUT_F32) { *(f32x4*)((float*)out + e) = v0; *(f32x4*)((float*)out + e + 4) = v1; }
;                     else { u32x4 w; w.x = cvt_pk_bf16(v0[0], v0[1]); w.y = cvt_pk_bf16(v0[2], v0[3]); w.z = cvt_pk_bf16(v1[0], v1[1]); w.w = cvt_pk_bf16(v1[2], v1[3]); *(u32x4*)((bf16_t*)out + e) = w; }
;                 }
; template <class Epi, bool ALIGN_EPI, class Hook = NoHook>
; __device__ __forceinline__ void gemm_phase(LAS unsigned char* lds, const Gemm g, const StaticOrder& S, const Epi& E, const Hook& HK = Hook()) {
;     ...
;         if (!has_next) break;
; #pragma unroll
;         for (int a = 0; a < 2; ++a)
; #pragma unroll
;             for (int b = 0; b < 2; ++b)
; #pragma unroll
;                 for (int m = 0; m < 4; ++m)
; #pragma unroll
;                     for (int n = 0; n < 2; ++n) acc[a][b][m][n] = (f32x4){0.f, 0.f, 0.f, 0.f};
;         cur = nxt; cA = nA; cB = nB; ++ui;
;         if constexpr (ALIGN_EPI) { if (wr == 1) PG8_BAR; }
	v_lshlrev_b32_e32 v116, 16, v78
	v_and_b32_e32 v117, 0xffff0000, v78
	v_lshlrev_b32_e32 v78, 16, v79
	v_and_b32_e32 v79, 0xffff0000, v79
	v_lshlrev_b32_e32 v118, 16, v80
	v_and_b32_e32 v119, 0xffff0000, v80
	v_lshl_add_u64 v[48:49], s[60:61], 0, v[48:49]
	v_lshlrev_b32_e32 v114, 16, v76
	v_and_b32_e32 v115, 0xffff0000, v76
	v_lshlrev_b32_e32 v76, 16, v77
	v_and_b32_e32 v77, 0xffff0000, v77
	v_lshlrev_b32_e32 v80, 16, v81
	v_and_b32_e32 v81, 0xffff0000, v81
	s_waitcnt vmcnt(7)
	v_lshlrev_b32_e32 v122, 16, v82
	v_and_b32_e32 v123, 0xffff0000, v82
	v_pk_fma_f32 v[46:47], v[50:51], 0.5, v[74:75] op_sel_hi:[1,0,1]
	v_lshl_add_u64 v[48:49], v[48:49], 0, v[120:121]
	v_pk_fma_f32 v[38:39], v[38:39], 0.5, v[78:79] op_sel_hi:[1,0,1]
	v_pk_fma_f32 v[36:37], v[36:37], 0.5, v[116:117] op_sel_hi:[1,0,1]
	v_pk_fma_f32 v[28:29], v[28:29], 0.5, v[118:119] op_sel_hi:[1,0,1]
	v_pk_fma_f32 v[42:43], v[42:43], 0.5, v[76:77] op_sel_hi:[1,0,1]
	v_pk_fma_f32 v[40:41], v[40:41], 0.5, v[114:115] op_sel_hi:[1,0,1]
	global_store_dwordx4 v[48:49], v[44:47], off
	global_store_dwordx4 v[48:49], v[40:43], off offset:16
	v_pk_fma_f32 v[30:31], v[30:31], 0.5, v[80:81] op_sel_hi:[1,0,1]
	global_store_dwordx4 v[48:49], v[36:39], off offset:512
	global_store_dwordx4 v[48:49], v[28:31], off offset:528
	v_lshlrev_b32_e32 v82, 16, v83
	v_and_b32_e32 v83, 0xffff0000, v83
	v_pk_fma_f32 v[28:29], v[32:33], 0.5, v[122:123] op_sel_hi:[1,0,1]
	v_lshlrev_b64 v[32:33], 13, v[102:103]
	s_waitcnt vmcnt(10)
	v_lshlrev_b32_e32 v126, 16, v86
	v_and_b32_e32 v127, 0xffff0000, v86
	v_lshlrev_b32_e32 v86, 16, v87
	v_and_b32_e32 v87, 0xffff0000, v87
	v_lshlrev_b32_e32 v144, 16, v88
	v_and_b32_e32 v145, 0xffff0000, v88
	v_lshl_add_u64 v[32:33], s[60:61], 0, v[32:33]
	v_lshlrev_b32_e32 v124, 16, v84
	v_and_b32_e32 v125, 0xffff0000, v84
	v_lshlrev_b32_e32 v84, 16, v85
	v_and_b32_e32 v85, 0xffff0000, v85
	v_lshlrev_b32_e32 v88, 16, v89
	v_and_b32_e32 v89, 0xffff0000, v89
	s_waitcnt vmcnt(9)
	v_lshlrev_b32_e32 v146, 16, v90
	v_and_b32_e32 v147, 0xffff0000, v90
	v_pk_fma_f32 v[30:31], v[34:35], 0.5, v[82:83] op_sel_hi:[1,0,1]
	v_lshl_add_u64 v[32:33], v[32:33], 0, v[120:121]
	v_pk_fma_f32 v[22:23], v[22:23], 0.5, v[86:87] op_sel_hi:[1,0,1]
	v_pk_fma_f32 v[20:21], v[20:21], 0.5, v[126:127] op_sel_hi:[1,0,1]
	v_pk_fma_f32 v[12:13], v[12:13], 0.5, v[144:145] op_sel_hi:[1,0,1]
	v_pk_fma_f32 v[26:27], v[26:27], 0.5, v[84:85] op_sel_hi:[1,0,1]
	v_pk_fma_f32 v[24:25], v[24:25], 0.5, v[124:125] op_sel_hi:[1,0,1]
	global_store_dwordx4 v[32:33], v[28:31], off
	global_store_dwordx4 v[32:33], v[24:27], off offset:16
	v_pk_fma_f32 v[14:15], v[14:15], 0.5, v[88:89] op_sel_hi:[1,0,1]
	global_store_dwordx4 v[32:33], v[20:23], off offset:512
	global_store_dwordx4 v[32:33], v[12:15], off offset:528
	v_lshlrev_b32_e32 v90, 16, v91
	v_and_b32_e32 v91, 0xffff0000, v91
	v_pk_fma_f32 v[12:13], v[16:17], 0.5, v[146:147] op_sel_hi:[1,0,1]
	v_lshlrev_b64 v[16:17], 13, v[64:65]
	s_waitcnt vmcnt(12)
	v_lshlrev_b32_e32 v156, 16, v94
	v_and_b32_e32 v157, 0xffff0000, v94
	v_lshlrev_b32_e32 v94, 16, v95
	v_and_b32_e32 v95, 0xffff0000, v95
	v_lshl_add_u64 v[16:17], s[60:61], 0, v[16:17]
	v_lshlrev_b32_e32 v148, 16, v92
	v_and_b32_e32 v149, 0xffff0000, v92
	v_lshlrev_b32_e32 v92, 16, v93
	v_and_b32_e32 v93, 0xffff0000, v93
	v_lshlrev_b32_e32 v158, 16, v96
	v_and_b32_e32 v159, 0xffff0000, v96
	v_lshlrev_b32_e32 v96, 16, v97
	v_and_b32_e32 v97, 0xffff0000, v97
	v_pk_fma_f32 v[14:15], v[18:19], 0.5, v[90:91] op_sel_hi:[1,0,1]
	v_lshl_add_u64 v[16:17], v[16:17], 0, v[120:121]
	v_pk_fma_f32 v[6:7], v[6:7], 0.5, v[94:95] op_sel_hi:[1,0,1]
	v_pk_fma_f32 v[4:5], v[4:5], 0.5, v[156:157] op_sel_hi:[1,0,1]
	v_pk_fma_f32 v[10:11], v[10:11], 0.5, v[92:93] op_sel_hi:[1,0,1]
	v_pk_fma_f32 v[8:9], v[8:9], 0.5, v[148:149] op_sel_hi:[1,0,1]
	global_store_dwordx4 v[16:17], v[12:15], off
	global_store_dwordx4 v[16:17], v[8:11], off offset:16
	v_pk_fma_f32 v[2:3], v[2:3], 0.5, v[96:97] op_sel_hi:[1,0,1]
	v_pk_fma_f32 v[0:1], v[0:1], 0.5, v[158:159] op_sel_hi:[1,0,1]
	global_store_dwordx4 v[16:17], v[4:7], off offset:512
	global_store_dwordx4 v[16:17], v[0:3], off offset:528
	s_cbranch_vccnz .LBB0_987
	s_andn2_b64 vcc, exec, s[6:7]
	s_cbranch_vccnz .LBB0_986
	s_branch .LBB0_986
